# GEMM<3> epilogue: residual loads (x, out0, gate) of all four row groups of a sub-tile prefetched into spare registers; original loads become moves behind counted waits
# speedup vs baseline: 1.0009x; 1.0009x over previous
.Lg24_loop:
	s_waitcnt lgkmcnt(4)
	v_mfma_f32_32x32x16_bf16 v[114:129], v[130:133], v[164:167], v[114:129]
	ds_read_b128 v[172:175], v204 offset:0
	s_waitcnt lgkmcnt(4)
	v_mfma_f32_32x32x16_bf16 v[98:113], v[130:133], v[168:171], v[98:113]
	ds_read_b128 v[192:195], v208 offset:0
	s_add_u32 m0, s14, 0x1a020
	s_add_u32 s12, s12, 0x40000
	s_addc_u32 s13, s13, 0
	global_load_lds_dwordx4 v155, s[12:13]
	s_waitcnt lgkmcnt(4)
	v_mfma_f32_32x32x16_bf16 v[82:97], v[134:137], v[164:167], v[82:97]
	ds_read_b128 v[200:203], v208 offset:4096
	v_mfma_f32_32x32x16_bf16 v[66:81], v[134:137], v[168:171], v[66:81]
	ds_read_b128 v[180:183], v204 offset:4096
	s_add_u32 m0, s14, 0x1c020
	s_add_u32 s12, s12, 0x40000
	s_addc_u32 s13, s13, 0
	global_load_lds_dwordx4 v155, s[12:13]
	s_waitcnt lgkmcnt(5)
	v_mfma_f32_32x32x16_bf16 v[50:65], v[156:159], v[164:167], v[50:65]
	ds_read_b128 v[184:187], v204 offset:8192
	v_mfma_f32_32x32x16_bf16 v[34:49], v[156:159], v[168:171], v[34:49]
	ds_read_b128 v[188:191], v204 offset:12288
	s_add_u32 m0, s14, 0x1e020
	s_add_u32 s12, s12, 0x40000
	s_addc_u32 s13, s13, 0
	global_load_lds_dwordx4 v155, s[12:13]
	s_add_u32 s4, s4, 0x80
	s_addc_u32 s5, s5, 0
	s_waitcnt lgkmcnt(6)
	v_mfma_f32_32x32x16_bf16 v[18:33], v[160:163], v[164:167], v[18:33]
	v_mfma_f32_32x32x16_bf16 v[2:17], v[160:163], v[168:171], v[2:17]
	s_waitcnt lgkmcnt(4)
	v_mfma_f32_32x32x16_bf16 v[114:129], v[172:175], v[192:195], v[114:129]
	ds_read_b128 v[130:133], v205 offset:0
	s_waitcnt lgkmcnt(4)
	v_mfma_f32_32x32x16_bf16 v[98:113], v[172:175], v[200:203], v[98:113]
	ds_read_b128 v[164:167], v209 offset:0
	s_waitcnt lgkmcnt(4)
	v_mfma_f32_32x32x16_bf16 v[82:97], v[180:183], v[192:195], v[82:97]
	ds_read_b128 v[168:171], v209 offset:4096
	v_mfma_f32_32x32x16_bf16 v[66:81], v[180:183], v[200:203], v[66:81]
	ds_read_b128 v[134:137], v205 offset:4096
	s_waitcnt lgkmcnt(5)
	v_mfma_f32_32x32x16_bf16 v[50:65], v[184:187], v[192:195], v[50:65]
	ds_read_b128 v[156:159], v205 offset:8192
	v_mfma_f32_32x32x16_bf16 v[34:49], v[184:187], v[200:203], v[34:49]
	ds_read_b128 v[160:163], v205 offset:12288
	s_waitcnt lgkmcnt(6)
	v_mfma_f32_32x32x16_bf16 v[18:33], v[188:191], v[192:195], v[18:33]
	v_mfma_f32_32x32x16_bf16 v[2:17], v[188:191], v[200:203], v[2:17]
	s_waitcnt lgkmcnt(4)
	v_mfma_f32_32x32x16_bf16 v[114:129], v[130:133], v[164:167], v[114:129]
	ds_read_b128 v[172:175], v206 offset:0
	ds_read_b128 v[192:195], v210 offset:0
	s_waitcnt lgkmcnt(5)
	v_mfma_f32_32x32x16_bf16 v[98:113], v[130:133], v[168:171], v[98:113]
	ds_read_b128 v[200:203], v210 offset:4096
	ds_read_b128 v[180:183], v206 offset:4096
	s_waitcnt lgkmcnt(6)
	v_mfma_f32_32x32x16_bf16 v[82:97], v[134:137], v[164:167], v[82:97]
	ds_read_b128 v[184:187], v206 offset:8192
	ds_read_b128 v[188:191], v206 offset:12288
	v_mfma_f32_32x32x16_bf16 v[66:81], v[134:137], v[168:171], v[66:81]
	s_waitcnt lgkmcnt(7)
	v_mfma_f32_32x32x16_bf16 v[50:65], v[156:159], v[164:167], v[50:65]
	v_mfma_f32_32x32x16_bf16 v[34:49], v[156:159], v[168:171], v[34:49]
	s_waitcnt lgkmcnt(6)
	v_mfma_f32_32x32x16_bf16 v[18:33], v[160:163], v[164:167], v[18:33]
	v_mfma_f32_32x32x16_bf16 v[2:17], v[160:163], v[168:171], v[2:17]
	s_waitcnt vmcnt(0) lgkmcnt(0)
	s_barrier
	v_mfma_f32_32x32x16_bf16 v[114:129], v[172:175], v[192:195], v[114:129]
	ds_read_b128 v[130:133], v177 offset:32768
	s_add_u32 m0, s14, 0x20
	s_add_u32 s12, s1, s4
	s_addc_u32 s13, s3, s5
	global_load_lds_dwordx4 v155, s[12:13]
	v_mfma_f32_32x32x16_bf16 v[98:113], v[172:175], v[200:203], v[98:113]
	ds_read_b128 v[164:167], v207 offset:32768
	s_add_u32 m0, s14, 0x2020
	s_add_u32 s12, s12, 0x40000
	s_addc_u32 s13, s13, 0
	global_load_lds_dwordx4 v155, s[12:13]
	v_mfma_f32_32x32x16_bf16 v[82:97], v[180:183], v[192:195], v[82:97]
	ds_read_b128 v[168:171], v207 offset:36864
	s_add_u32 m0, s14, 0x4020
	s_add_u32 s12, s12, 0x40000
	s_addc_u32 s13, s13, 0
	global_load_lds_dwordx4 v155, s[12:13]
	v_mfma_f32_32x32x16_bf16 v[66:81], v[180:183], v[200:203], v[66:81]
	ds_read_b128 v[134:137], v177 offset:36864
	s_add_u32 m0, s14, 0x6020
	s_add_u32 s12, s12, 0x40000
	s_addc_u32 s13, s13, 0
	global_load_lds_dwordx4 v155, s[12:13]
	v_mfma_f32_32x32x16_bf16 v[50:65], v[184:187], v[192:195], v[50:65]
	ds_read_b128 v[156:159], v177 offset:40960
	s_add_u32 m0, s14, 0x10020
	s_add_u32 s12, s9, s4
	s_addc_u32 s13, s10, s5
	global_load_lds_dwordx4 v155, s[12:13]
	v_mfma_f32_32x32x16_bf16 v[34:49], v[184:187], v[200:203], v[34:49]
	ds_read_b128 v[160:163], v177 offset:45056
	v_mfma_f32_32x32x16_bf16 v[18:33], v[188:191], v[192:195], v[18:33]
	v_mfma_f32_32x32x16_bf16 v[2:17], v[188:191], v[200:203], v[2:17]
	s_waitcnt lgkmcnt(4)
	v_mfma_f32_32x32x16_bf16 v[114:129], v[130:133], v[164:167], v[114:129]
	ds_read_b128 v[172:175], v204 offset:32768
	s_waitcnt lgkmcnt(4)
	v_mfma_f32_32x32x16_bf16 v[98:113], v[130:133], v[168:171], v[98:113]
	ds_read_b128 v[192:195], v208 offset:32768
	s_add_u32 m0, s14, 0x12020
	s_add_u32 s12, s12, 0x40000
	s_addc_u32 s13, s13, 0
	global_load_lds_dwordx4 v155, s[12:13]
	s_waitcnt lgkmcnt(4)
	v_mfma_f32_32x32x16_bf16 v[82:97], v[134:137], v[164:167], v[82:97]
	ds_read_b128 v[200:203], v208 offset:36864
	v_mfma_f32_32x32x16_bf16 v[66:81], v[134:137], v[168:171], v[66:81]
	ds_read_b128 v[180:183], v204 offset:36864
	s_add_u32 m0, s14, 0x14020
	s_add_u32 s12, s12, 0x40000
	s_addc_u32 s13, s13, 0
	global_load_lds_dwordx4 v155, s[12:13]
	s_waitcnt lgkmcnt(5)
	v_mfma_f32_32x32x16_bf16 v[50:65], v[156:159], v[164:167], v[50:65]
	ds_read_b128 v[184:187], v204 offset:40960
	v_mfma_f32_32x32x16_bf16 v[34:49], v[156:159], v[168:171], v[34:49]
	ds_read_b128 v[188:191], v204 offset:45056
	s_add_u32 m0, s14, 0x16020
	s_add_u32 s12, s12, 0x40000
	s_addc_u32 s13, s13, 0
	global_load_lds_dwordx4 v155, s[12:13]
	s_add_u32 s4, s4, 0x80
	s_addc_u32 s5, s5, 0
	s_waitcnt lgkmcnt(6)
	v_mfma_f32_32x32x16_bf16 v[18:33], v[160:163], v[164:167], v[18:33]
	v_mfma_f32_32x32x16_bf16 v[2:17], v[160:163], v[168:171], v[2:17]
	s_waitcnt lgkmcnt(4)
	v_mfma_f32_32x32x16_bf16 v[114:129], v[172:175], v[192:195], v[114:129]
	ds_read_b128 v[130:133], v205 offset:32768
	s_waitcnt lgkmcnt(4)
	v_mfma_f32_32x32x16_bf16 v[98:113], v[172:175], v[200:203], v[98:113]
	ds_read_b128 v[164:167], v209 offset:32768
	s_waitcnt lgkmcnt(4)
	v_mfma_f32_32x32x16_bf16 v[82:97], v[180:183], v[192:195], v[82:97]
	ds_read_b128 v[168:171], v209 offset:36864
	v_mfma_f32_32x32x16_bf16 v[66:81], v[180:183], v[200:203], v[66:81]
	ds_read_b128 v[134:137], v205 offset:36864
	s_waitcnt lgkmcnt(5)
	v_mfma_f32_32x32x16_bf16 v[50:65], v[184:187], v[192:195], v[50:65]
	ds_read_b128 v[156:159], v205 offset:40960
	v_mfma_f32_32x32x16_bf16 v[34:49], v[184:187], v[200:203], v[34:49]
	ds_read_b128 v[160:163], v205 offset:45056
	s_waitcnt lgkmcnt(6)
	v_mfma_f32_32x32x16_bf16 v[18:33], v[188:191], v[192:195], v[18:33]
	v_mfma_f32_32x32x16_bf16 v[2:17], v[188:191], v[200:203], v[2:17]
	s_waitcnt lgkmcnt(4)
	v_mfma_f32_32x32x16_bf16 v[114:129], v[130:133], v[164:167], v[114:129]
	ds_read_b128 v[172:175], v206 offset:32768
	ds_read_b128 v[192:195], v210 offset:32768
	s_waitcnt lgkmcnt(5)
	v_mfma_f32_32x32x16_bf16 v[98:113], v[130:133], v[168:171], v[98:113]
	ds_read_b128 v[200:203], v210 offset:36864
	ds_read_b128 v[180:183], v206 offset:36864
	s_waitcnt lgkmcnt(6)
	v_mfma_f32_32x32x16_bf16 v[82:97], v[134:137], v[164:167], v[82:97]
	ds_read_b128 v[184:187], v206 offset:40960
	ds_read_b128 v[188:191], v206 offset:45056
	v_mfma_f32_32x32x16_bf16 v[66:81], v[134:137], v[168:171], v[66:81]
	s_waitcnt lgkmcnt(7)
	v_mfma_f32_32x32x16_bf16 v[50:65], v[156:159], v[164:167], v[50:65]
	v_mfma_f32_32x32x16_bf16 v[34:49], v[156:159], v[168:171], v[34:49]
	s_waitcnt lgkmcnt(6)
	v_mfma_f32_32x32x16_bf16 v[18:33], v[160:163], v[164:167], v[18:33]
	v_mfma_f32_32x32x16_bf16 v[2:17], v[160:163], v[168:171], v[2:17]
	s_waitcnt vmcnt(0) lgkmcnt(0)
	s_barrier
	v_mfma_f32_32x32x16_bf16 v[114:129], v[172:175], v[192:195], v[114:129]
	ds_read_b128 v[130:133], v177 offset:0
	s_add_u32 m0, s14, 0x8020
	s_add_u32 s12, s1, s4
	s_addc_u32 s13, s3, s5
	global_load_lds_dwordx4 v155, s[12:13]
	v_mfma_f32_32x32x16_bf16 v[98:113], v[172:175], v[200:203], v[98:113]
	ds_read_b128 v[164:167], v207 offset:0
	s_add_u32 m0, s14, 0xa020
	s_add_u32 s12, s12, 0x40000
	s_addc_u32 s13, s13, 0
	global_load_lds_dwordx4 v155, s[12:13]
	v_mfma_f32_32x32x16_bf16 v[82:97], v[180:183], v[192:195], v[82:97]
	ds_read_b128 v[168:171], v207 offset:4096
	s_add_u32 m0, s14, 0xc020
	s_add_u32 s12, s12, 0x40000
	s_addc_u32 s13, s13, 0
	global_load_lds_dwordx4 v155, s[12:13]
	v_mfma_f32_32x32x16_bf16 v[66:81], v[180:183], v[200:203], v[66:81]
	ds_read_b128 v[134:137], v177 offset:4096
	s_add_u32 m0, s14, 0xe020
	s_add_u32 s12, s12, 0x40000
	s_addc_u32 s13, s13, 0
	global_load_lds_dwordx4 v155, s[12:13]
	v_mfma_f32_32x32x16_bf16 v[50:65], v[184:187], v[192:195], v[50:65]
	ds_read_b128 v[156:159], v177 offset:8192
	s_add_u32 m0, s14, 0x18020
	s_add_u32 s12, s9, s4
	s_addc_u32 s13, s10, s5
	global_load_lds_dwordx4 v155, s[12:13]
	v_mfma_f32_32x32x16_bf16 v[34:49], v[184:187], v[200:203], v[34:49]
	ds_read_b128 v[160:163], v177 offset:12288
	v_mfma_f32_32x32x16_bf16 v[18:33], v[188:191], v[192:195], v[18:33]
	v_mfma_f32_32x32x16_bf16 v[2:17], v[188:191], v[200:203], v[2:17]
	s_sub_u32 s11, s11, 1
	s_cmp_lg_u32 s11, 0
	s_cbranch_scc1 .Lg24_loop
	s_waitcnt lgkmcnt(4)
	v_mfma_f32_32x32x16_bf16 v[114:129], v[130:133], v[164:167], v[114:129]
	ds_read_b128 v[172:175], v204 offset:0
	s_waitcnt lgkmcnt(4)
	v_mfma_f32_32x32x16_bf16 v[98:113], v[130:133], v[168:171], v[98:113]
	ds_read_b128 v[192:195], v208 offset:0
	s_add_u32 m0, s14, 0x1a020
	s_add_u32 s12, s12, 0x40000
	s_addc_u32 s13, s13, 0
	global_load_lds_dwordx4 v155, s[12:13]
	s_waitcnt lgkmcnt(4)
	v_mfma_f32_32x32x16_bf16 v[82:97], v[134:137], v[164:167], v[82:97]
	ds_read_b128 v[200:203], v208 offset:4096
	v_mfma_f32_32x32x16_bf16 v[66:81], v[134:137], v[168:171], v[66:81]
	ds_read_b128 v[180:183], v204 offset:4096
	s_add_u32 m0, s14, 0x1c020
	s_add_u32 s12, s12, 0x40000
	s_addc_u32 s13, s13, 0
	global_load_lds_dwordx4 v155, s[12:13]
	s_waitcnt lgkmcnt(5)
	v_mfma_f32_32x32x16_bf16 v[50:65], v[156:159], v[164:167], v[50:65]
	ds_read_b128 v[184:187], v204 offset:8192
	v_mfma_f32_32x32x16_bf16 v[34:49], v[156:159], v[168:171], v[34:49]
	ds_read_b128 v[188:191], v204 offset:12288
	s_add_u32 m0, s14, 0x1e020
	s_add_u32 s12, s12, 0x40000
	s_addc_u32 s13, s13, 0
	global_load_lds_dwordx4 v155, s[12:13]
	s_add_u32 s4, s4, 0x80
	s_addc_u32 s5, s5, 0
	s_waitcnt lgkmcnt(6)
	v_mfma_f32_32x32x16_bf16 v[18:33], v[160:163], v[164:167], v[18:33]
	v_mfma_f32_32x32x16_bf16 v[2:17], v[160:163], v[168:171], v[2:17]
	s_waitcnt lgkmcnt(4)
	v_mfma_f32_32x32x16_bf16 v[114:129], v[172:175], v[192:195], v[114:129]
	ds_read_b128 v[130:133], v205 offset:0
	s_waitcnt lgkmcnt(4)
	v_mfma_f32_32x32x16_bf16 v[98:113], v[172:175], v[200:203], v[98:113]
	ds_read_b128 v[164:167], v209 offset:0
	s_waitcnt lgkmcnt(4)
	v_mfma_f32_32x32x16_bf16 v[82:97], v[180:183], v[192:195], v[82:97]
	ds_read_b128 v[168:171], v209 offset:4096
	v_mfma_f32_32x32x16_bf16 v[66:81], v[180:183], v[200:203], v[66:81]
	ds_read_b128 v[134:137], v205 offset:4096
	s_waitcnt lgkmcnt(5)
	v_mfma_f32_32x32x16_bf16 v[50:65], v[184:187], v[192:195], v[50:65]
	ds_read_b128 v[156:159], v205 offset:8192
	v_mfma_f32_32x32x16_bf16 v[34:49], v[184:187], v[200:203], v[34:49]
	ds_read_b128 v[160:163], v205 offset:12288
	s_waitcnt lgkmcnt(6)
	v_mfma_f32_32x32x16_bf16 v[18:33], v[188:191], v[192:195], v[18:33]
	v_mfma_f32_32x32x16_bf16 v[2:17], v[188:191], v[200:203], v[2:17]
	s_waitcnt lgkmcnt(4)
	v_mfma_f32_32x32x16_bf16 v[114:129], v[130:133], v[164:167], v[114:129]
	ds_read_b128 v[172:175], v206 offset:0
	ds_read_b128 v[192:195], v210 offset:0
	s_waitcnt lgkmcnt(5)
	v_mfma_f32_32x32x16_bf16 v[98:113], v[130:133], v[168:171], v[98:113]
	ds_read_b128 v[200:203], v210 offset:4096
	ds_read_b128 v[180:183], v206 offset:4096
	s_waitcnt lgkmcnt(6)
	v_mfma_f32_32x32x16_bf16 v[82:97], v[134:137], v[164:167], v[82:97]
	ds_read_b128 v[184:187], v206 offset:8192
	ds_read_b128 v[188:191], v206 offset:12288
	v_mfma_f32_32x32x16_bf16 v[66:81], v[134:137], v[168:171], v[66:81]
	s_waitcnt lgkmcnt(7)
	v_mfma_f32_32x32x16_bf16 v[50:65], v[156:159], v[164:167], v[50:65]
	v_mfma_f32_32x32x16_bf16 v[34:49], v[156:159], v[168:171], v[34:49]
	s_waitcnt lgkmcnt(6)
	v_mfma_f32_32x32x16_bf16 v[18:33], v[160:163], v[164:167], v[18:33]
	v_mfma_f32_32x32x16_bf16 v[2:17], v[160:163], v[168:171], v[2:17]
	s_waitcnt vmcnt(0) lgkmcnt(0)
	s_barrier
	v_mfma_f32_32x32x16_bf16 v[114:129], v[172:175], v[192:195], v[114:129]
	ds_read_b128 v[130:133], v177 offset:32768
	v_mfma_f32_32x32x16_bf16 v[98:113], v[172:175], v[200:203], v[98:113]
	ds_read_b128 v[164:167], v207 offset:32768
	v_mfma_f32_32x32x16_bf16 v[82:97], v[180:183], v[192:195], v[82:97]
	ds_read_b128 v[168:171], v207 offset:36864
	v_mfma_f32_32x32x16_bf16 v[66:81], v[180:183], v[200:203], v[66:81]
	ds_read_b128 v[134:137], v177 offset:36864
	v_mfma_f32_32x32x16_bf16 v[50:65], v[184:187], v[192:195], v[50:65]
	ds_read_b128 v[156:159], v177 offset:40960
	v_mfma_f32_32x32x16_bf16 v[34:49], v[184:187], v[200:203], v[34:49]
	ds_read_b128 v[160:163], v177 offset:45056
	v_mfma_f32_32x32x16_bf16 v[18:33], v[188:191], v[192:195], v[18:33]
	v_mfma_f32_32x32x16_bf16 v[2:17], v[188:191], v[200:203], v[2:17]
	s_waitcnt lgkmcnt(4)
	v_mfma_f32_32x32x16_bf16 v[114:129], v[130:133], v[164:167], v[114:129]
	ds_read_b128 v[172:175], v204 offset:32768
	s_waitcnt lgkmcnt(4)
	v_mfma_f32_32x32x16_bf16 v[98:113], v[130:133], v[168:171], v[98:113]
	ds_read_b128 v[192:195], v208 offset:32768
	s_waitcnt lgkmcnt(4)
	v_mfma_f32_32x32x16_bf16 v[82:97], v[134:137], v[164:167], v[82:97]
	ds_read_b128 v[200:203], v208 offset:36864
	v_mfma_f32_32x32x16_bf16 v[66:81], v[134:137], v[168:171], v[66:81]
	ds_read_b128 v[180:183], v204 offset:36864
	s_waitcnt lgkmcnt(5)
	v_mfma_f32_32x32x16_bf16 v[50:65], v[156:159], v[164:167], v[50:65]
	ds_read_b128 v[184:187], v204 offset:40960
	v_mfma_f32_32x32x16_bf16 v[34:49], v[156:159], v[168:171], v[34:49]
	ds_read_b128 v[188:191], v204 offset:45056
	s_waitcnt lgkmcnt(6)
	v_mfma_f32_32x32x16_bf16 v[18:33], v[160:163], v[164:167], v[18:33]
	v_mfma_f32_32x32x16_bf16 v[2:17], v[160:163], v[168:171], v[2:17]
	s_waitcnt lgkmcnt(4)
	v_mfma_f32_32x32x16_bf16 v[114:129], v[172:175], v[192:195], v[114:129]
	ds_read_b128 v[130:133], v205 offset:32768
	s_waitcnt lgkmcnt(4)
	v_mfma_f32_32x32x16_bf16 v[98:113], v[172:175], v[200:203], v[98:113]
	ds_read_b128 v[164:167], v209 offset:32768
	s_waitcnt lgkmcnt(4)
	v_mfma_f32_32x32x16_bf16 v[82:97], v[180:183], v[192:195], v[82:97]
	ds_read_b128 v[168:171], v209 offset:36864
	v_mfma_f32_32x32x16_bf16 v[66:81], v[180:183], v[200:203], v[66:81]
	ds_read_b128 v[134:137], v205 offset:36864
	s_waitcnt lgkmcnt(5)
	v_mfma_f32_32x32x16_bf16 v[50:65], v[184:187], v[192:195], v[50:65]
	ds_read_b128 v[156:159], v205 offset:40960
	v_mfma_f32_32x32x16_bf16 v[34:49], v[184:187], v[200:203], v[34:49]
	ds_read_b128 v[160:163], v205 offset:45056
	s_waitcnt lgkmcnt(6)
	v_mfma_f32_32x32x16_bf16 v[18:33], v[188:191], v[192:195], v[18:33]
	v_mfma_f32_32x32x16_bf16 v[2:17], v[188:191], v[200:203], v[2:17]
	s_waitcnt lgkmcnt(4)
	v_mfma_f32_32x32x16_bf16 v[114:129], v[130:133], v[164:167], v[114:129]
	ds_read_b128 v[172:175], v206 offset:32768
	ds_read_b128 v[192:195], v210 offset:32768
	s_waitcnt lgkmcnt(5)
	v_mfma_f32_32x32x16_bf16 v[98:113], v[130:133], v[168:171], v[98:113]
	ds_read_b128 v[200:203], v210 offset:36864
	ds_read_b128 v[180:183], v206 offset:36864
	s_waitcnt lgkmcnt(6)
	v_mfma_f32_32x32x16_bf16 v[82:97], v[134:137], v[164:167], v[82:97]
	ds_read_b128 v[184:187], v206 offset:40960
	ds_read_b128 v[188:191], v206 offset:45056
	v_mfma_f32_32x32x16_bf16 v[66:81], v[134:137], v[168:171], v[66:81]
	s_waitcnt lgkmcnt(7)
	v_mfma_f32_32x32x16_bf16 v[50:65], v[156:159], v[164:167], v[50:65]
	v_mfma_f32_32x32x16_bf16 v[34:49], v[156:159], v[168:171], v[34:49]
	s_waitcnt lgkmcnt(6)
	v_mfma_f32_32x32x16_bf16 v[18:33], v[160:163], v[164:167], v[18:33]
	v_mfma_f32_32x32x16_bf16 v[2:17], v[160:163], v[168:171], v[2:17]
	s_waitcnt vmcnt(0) lgkmcnt(0)
	s_barrier
	v_mfma_f32_32x32x16_bf16 v[114:129], v[172:175], v[192:195], v[114:129]
	v_mfma_f32_32x32x16_bf16 v[98:113], v[172:175], v[200:203], v[98:113]
	v_mfma_f32_32x32x16_bf16 v[82:97], v[180:183], v[192:195], v[82:97]
	v_mfma_f32_32x32x16_bf16 v[66:81], v[180:183], v[200:203], v[66:81]
	v_mfma_f32_32x32x16_bf16 v[50:65], v[184:187], v[192:195], v[50:65]
	v_mfma_f32_32x32x16_bf16 v[34:49], v[184:187], v[200:203], v[34:49]
	v_mfma_f32_32x32x16_bf16 v[18:33], v[188:191], v[192:195], v[18:33]
	v_mfma_f32_32x32x16_bf16 v[2:17], v[188:191], v[200:203], v[2:17]
	v_add_u32_e32 v130, s0, v149
	v_ashrrev_i32_e32 v131, 31, v130
	v_lshrrev_b32_e32 v155, 18, v131
	v_add_u32_e32 v0, v130, v155
	v_ashrrev_i32_e32 v0, 14, v0
	v_mul_i32_i24_e32 v133, 0x4000, v0
	v_sub_u32_e32 v133, v130, v133
	v_add_u32_e32 v156, 0x100, v133
	v_mul_hi_i32_i24_e32 v137, 0x4100, v0
	v_mul_i32_i24_e32 v136, 0x4100, v0
	v_ashrrev_i32_e32 v157, 31, v156
	v_lshl_add_u64 v[136:137], v[136:137], 0, v[156:157]
	v_mov_b32_e32 v156, v179
	s_waitcnt vmcnt(0)
	s_barrier
	v_mul_i32_i24_e32 v134, 0xc00, v0
	v_readlane_b32 s40, v251, 2
	v_and_b32_e32 v0, 31, v156
	v_bfe_u32 v133, v156, 5, 1
	v_mul_u32_u24_e32 v133, 0x240, v133
	v_lshlrev_b32_e32 v0, 2, v0
	v_add3_u32 v0, v151, v133, v0
	ds_write2_b32 v0, v114, v115 offset1:36
	ds_write2_b32 v0, v116, v117 offset0:72 offset1:108
	v_add_u32_e32 v114, 0x400, v0
	v_or_b32_e32 v132, s2, v150
	ds_write2_b32 v114, v118, v119 offset0:32 offset1:68
	ds_write2_b32 v114, v120, v121 offset0:104 offset1:140
	v_add_u32_e32 v114, 0x800, v0
	v_add_u32_e32 v0, 0xc00, v0
	v_readlane_b32 s41, v251, 3
	v_readlane_b32 s42, v251, 4
	v_readlane_b32 s43, v251, 5
	v_readlane_b32 s44, v251, 6
	v_readlane_b32 s45, v251, 7
	v_readlane_b32 s46, v251, 8
	v_readlane_b32 s47, v251, 9
	v_readlane_b32 s48, v251, 10
	v_readlane_b32 s49, v251, 11
	v_readlane_b32 s50, v251, 12
	v_readlane_b32 s51, v251, 13
	v_readlane_b32 s0, v251, 26
	v_ashrrev_i32_e32 v135, 31, v134
	v_lshlrev_b64 v[136:137], 11, v[136:137]
	ds_write2_b32 v114, v122, v123 offset0:64 offset1:100
	ds_write2_b32 v114, v124, v125 offset0:136 offset1:172
	ds_write2_b32 v0, v126, v127 offset0:96 offset1:132
	ds_write2_b32 v0, v128, v129 offset0:168 offset1:204
	v_readlane_b32 s54, v251, 16
	v_readlane_b32 s55, v251, 17
	v_ashrrev_i32_e32 v133, 31, v132
	v_readlane_b32 s1, v251, 27
	v_readlane_b32 s36, v253, 47
	v_lshlrev_b32_e32 v0, 2, v156
	v_readlane_b32 s52, v251, 14
	v_readlane_b32 s53, v251, 15
	v_lshl_add_u64 v[114:115], v[134:135], 2, s[54:55]
	s_mov_b64 s[2:3], 0x1b0b000
	v_lshl_add_u64 v[118:119], s[0:1], 0, v[136:137]
	v_lshlrev_b64 v[116:117], 1, v[132:133]
	v_lshlrev_b64 v[122:123], 12, v[130:131]
	v_readlane_b32 s37, v253, 48
	v_and_b32_e32 v128, 28, v0
	v_lshl_add_u64 v[120:121], v[114:115], 0, s[2:3]
	v_lshlrev_b64 v[114:115], 2, v[132:133]
	v_lshl_add_u64 v[118:119], v[118:119], 0, v[116:117]
	v_lshl_add_u64 v[124:125], s[36:37], 0, v[122:123]
	v_lshl_add_u64 v[122:123], s[52:53], 0, v[122:123]
	v_lshlrev_b32_e32 v0, 2, v128
	v_lshlrev_b32_e32 v128, 1, v128
	v_mov_b32_e32 v129, v1
	v_bfe_u32 v133, v156, 3, 3
	v_lshl_add_u64 v[126:127], v[120:121], 0, v[114:115]
	v_lshl_add_u64 v[124:125], v[124:125], 0, v[114:115]
	v_lshl_add_u64 v[122:123], v[122:123], 0, v[114:115]
	v_lshl_add_u64 v[134:135], v[118:119], 0, v[128:129]
	v_mul_u32_u24_e32 v131, 0x90, v133
	v_lshlrev_b32_e32 v156, 11, v133
	v_mov_b32_e32 v157, v1
	s_waitcnt lgkmcnt(0)
	v_lshl_add_u64 v[126:127], v[126:127], 0, v[0:1]
	v_lshl_add_u64 v[136:137], v[124:125], 0, v[0:1]
	v_lshl_add_u64 v[128:129], v[122:123], 0, v[0:1]
	v_add3_u32 v131, v151, v0, v131
	v_lshlrev_b32_e32 v0, 12, v133
	v_lshl_add_u64 v[156:157], v[134:135], 0, v[156:157]
	v_lshl_add_u64 v[164:165], v[136:137], 0, v[0:1]
	global_load_dwordx4 v[180:183], v[126:127], off
	v_mov_b32_e32 v212, v133
	v_lshlrev_b32_e32 v184, 11, v212
	v_mov_b32_e32 v185, v1
	v_lshl_add_u64 v[184:185], v[134:135], 0, v[184:185]
	global_load_dwordx2 v[184:185], v[184:185], off
	v_lshlrev_b32_e32 v192, 12, v212
	v_mov_b32_e32 v193, v1
	v_lshl_add_u64 v[192:193], v[136:137], 0, v[192:193]
	global_load_dwordx4 v[192:195], v[192:193], off
	v_or_b32_e32 v212, 8, v133
	v_lshlrev_b32_e32 v186, 11, v212
	v_mov_b32_e32 v187, v1
	v_lshl_add_u64 v[186:187], v[134:135], 0, v[186:187]
	global_load_dwordx2 v[186:187], v[186:187], off
	v_lshlrev_b32_e32 v200, 12, v212
	v_mov_b32_e32 v201, v1
	v_lshl_add_u64 v[200:201], v[136:137], 0, v[200:201]
	global_load_dwordx4 v[200:203], v[200:201], off
	v_or_b32_e32 v212, 16, v133
	v_lshlrev_b32_e32 v188, 11, v212
	v_mov_b32_e32 v189, v1
	v_lshl_add_u64 v[188:189], v[134:135], 0, v[188:189]
	global_load_dwordx2 v[188:189], v[188:189], off
	v_lshlrev_b32_e32 v204, 12, v212
	v_mov_b32_e32 v205, v1
	v_lshl_add_u64 v[204:205], v[136:137], 0, v[204:205]
	global_load_dwordx4 v[204:207], v[204:205], off
	v_or_b32_e32 v212, 24, v133
	v_lshlrev_b32_e32 v190, 11, v212
	v_mov_b32_e32 v191, v1
	v_lshl_add_u64 v[190:191], v[134:135], 0, v[190:191]
	global_load_dwordx2 v[190:191], v[190:191], off
	v_lshlrev_b32_e32 v208, 12, v212
	v_mov_b32_e32 v209, v1
	v_lshl_add_u64 v[208:209], v[136:137], 0, v[208:209]
	global_load_dwordx4 v[208:211], v[208:209], off
	s_waitcnt vmcnt(6)
	v_mov_b32_e32 v168, v184
	v_mov_b32_e32 v169, v185
	ds_read_b128 v[156:159], v131
	v_mov_b32_e32 v160, v180
	v_mov_b32_e32 v161, v181
	v_mov_b32_e32 v162, v182
	v_mov_b32_e32 v163, v183
	s_nop 0
	v_mov_b32_e32 v164, v192
	v_mov_b32_e32 v165, v193
	v_mov_b32_e32 v166, v194
	v_mov_b32_e32 v167, v195
	v_lshl_add_u64 v[170:171], v[128:129], 0, v[0:1]
	v_readlane_b32 s38, v253, 49
	v_readlane_b32 s39, v253, 50
	v_readlane_b32 s42, v253, 53
	v_readlane_b32 s43, v253, 54
	v_readlane_b32 s44, v253, 55
	v_readlane_b32 s45, v253, 56
	v_readlane_b32 s46, v253, 57
	v_readlane_b32 s47, v253, 58
	v_readlane_b32 s48, v253, 59
	v_readlane_b32 s49, v253, 60
	v_readlane_b32 s51, v253, 62
	v_readlane_b32 s40, v253, 51
	v_readlane_b32 s41, v253, 52
	v_readlane_b32 s50, v253, 61
	v_and_b32_e32 v173, 0xffff0000, v168
	v_lshlrev_b32_e32 v172, 16, v168
	v_pk_add_f32 v[164:165], v[164:165], v[172:173]
	s_waitcnt lgkmcnt(0)
	v_pk_fma_f32 v[156:157], v[156:157], v[160:161], v[164:165]
	v_and_b32_e32 v161, 0xffff0000, v169
	v_lshlrev_b32_e32 v160, 16, v169
	v_pk_add_f32 v[160:161], v[166:167], v[160:161]
	s_nop 0
	v_pk_fma_f32 v[158:159], v[158:159], v[162:163], v[160:161]
	global_store_dwordx4 v[170:171], v[156:159], off
	s_nop 1
	v_or_b32_e32 v156, 8, v133
	v_lshlrev_b32_e32 v0, 12, v156
	v_lshlrev_b32_e32 v156, 11, v156
	v_mov_b32_e32 v157, v1
	v_lshl_add_u64 v[156:157], v[134:135], 0, v[156:157]
	v_lshl_add_u64 v[164:165], v[136:137], 0, v[0:1]
	s_waitcnt vmcnt(5)
	v_mov_b32_e32 v168, v186
	v_mov_b32_e32 v169, v187
	ds_read_b128 v[156:159], v131 offset:1152
	v_mov_b32_e32 v160, v180
	v_mov_b32_e32 v161, v181
	v_mov_b32_e32 v162, v182
	v_mov_b32_e32 v163, v183
	s_nop 0
	v_mov_b32_e32 v164, v200
	v_mov_b32_e32 v165, v201
	v_mov_b32_e32 v166, v202
	v_mov_b32_e32 v167, v203
	v_lshl_add_u64 v[170:171], v[128:129], 0, v[0:1]
	v_or_b32_e32 v0, 16, v133
	v_and_b32_e32 v173, 0xffff0000, v168
	v_lshlrev_b32_e32 v172, 16, v168
	v_pk_add_f32 v[164:165], v[164:165], v[172:173]
	s_waitcnt lgkmcnt(0)
	v_pk_fma_f32 v[156:157], v[156:157], v[160:161], v[164:165]
	v_and_b32_e32 v161, 0xffff0000, v169
	v_lshlrev_b32_e32 v160, 16, v169
	v_pk_add_f32 v[160:161], v[166:167], v[160:161]
	s_nop 0
	v_pk_fma_f32 v[158:159], v[158:159], v[162:163], v[160:161]
	global_store_dwordx4 v[170:171], v[156:159], off
	s_nop 1
	v_lshlrev_b32_e32 v158, 11, v0
	v_mov_b32_e32 v159, v1
	v_lshlrev_b32_e32 v156, 12, v0
	v_mov_b32_e32 v157, v1
	v_lshl_add_u64 v[158:159], v[134:135], 0, v[158:159]
	v_lshl_add_u64 v[164:165], v[136:137], 0, v[156:157]
	s_waitcnt vmcnt(4)
	v_mov_b32_e32 v168, v188
	v_mov_b32_e32 v169, v189
	v_lshl_add_u64 v[170:171], v[128:129], 0, v[156:157]
	ds_read_b128 v[156:159], v131 offset:2304
	v_mov_b32_e32 v160, v180
	v_mov_b32_e32 v161, v181
	v_mov_b32_e32 v162, v182
	v_mov_b32_e32 v163, v183
	s_nop 0
	v_mov_b32_e32 v164, v204
	v_mov_b32_e32 v165, v205
	v_mov_b32_e32 v166, v206
	v_mov_b32_e32 v167, v207
	v_or_b32_e32 v0, 24, v133
	v_and_b32_e32 v173, 0xffff0000, v168
	v_lshlrev_b32_e32 v172, 16, v168
	v_pk_add_f32 v[164:165], v[164:165], v[172:173]
	s_waitcnt lgkmcnt(0)
	v_pk_fma_f32 v[156:157], v[156:157], v[160:161], v[164:165]
	v_and_b32_e32 v161, 0xffff0000, v169
	v_lshlrev_b32_e32 v160, 16, v169
	v_pk_add_f32 v[160:161], v[166:167], v[160:161]
	s_nop 0
	v_pk_fma_f32 v[158:159], v[158:159], v[162:163], v[160:161]
	global_store_dwordx4 v[170:171], v[156:159], off
	s_nop 1
	v_lshlrev_b32_e32 v156, 12, v0
	v_mov_b32_e32 v157, v1
	v_lshl_add_u64 v[158:159], v[136:137], 0, v[156:157]
	v_lshlrev_b32_e32 v136, 11, v0
	v_mov_b32_e32 v137, v1
	v_lshl_add_u64 v[134:135], v[134:135], 0, v[136:137]
	s_waitcnt vmcnt(3)
	v_mov_b32_e32 v160, v190
	v_mov_b32_e32 v161, v191
	v_lshl_add_u64 v[162:163], v[128:129], 0, v[156:157]
	ds_read_b128 v[134:137], v131 offset:3456
	v_mov_b32_e32 v126, v180
	v_mov_b32_e32 v127, v181
	v_mov_b32_e32 v128, v182
	v_mov_b32_e32 v129, v183
	s_nop 0
	v_mov_b32_e32 v156, v208
	v_mov_b32_e32 v157, v209
	v_mov_b32_e32 v158, v210
	v_mov_b32_e32 v159, v211
	v_and_b32_e32 v165, 0xffff0000, v160
	v_lshlrev_b32_e32 v164, 16, v160
	v_pk_add_f32 v[156:157], v[156:157], v[164:165]
	s_waitcnt lgkmcnt(0)
	v_pk_fma_f32 v[126:127], v[134:135], v[126:127], v[156:157]
	v_and_b32_e32 v135, 0xffff0000, v161
	v_lshlrev_b32_e32 v134, 16, v161
	v_pk_add_f32 v[134:135], v[158:159], v[134:135]
	s_nop 0
	v_pk_fma_f32 v[128:129], v[136:137], v[128:129], v[134:135]
	global_store_dwordx4 v[162:163], v[126:129], off
	v_mov_b32_e32 v0, v179
	s_nop 0
	v_or_b32_e32 v126, 32, v132
	v_and_b32_e32 v127, 31, v0
	v_bfe_u32 v128, v0, 5, 1
	v_mul_u32_u24_e32 v128, 0x240, v128
	v_lshlrev_b32_e32 v127, 2, v127
	v_add3_u32 v127, v151, v128, v127
	ds_write2_b32 v127, v98, v99 offset1:36
	ds_write2_b32 v127, v100, v101 offset0:72 offset1:108
	v_add_u32_e32 v98, 0x400, v127
	ds_write2_b32 v98, v102, v103 offset0:32 offset1:68
	ds_write2_b32 v98, v104, v105 offset0:104 offset1:140
	v_add_u32_e32 v98, 0x800, v127
	ds_write2_b32 v98, v106, v107 offset0:64 offset1:100
	ds_write2_b32 v98, v108, v109 offset0:136 offset1:172
	v_add_u32_e32 v98, 0xc00, v127
	ds_write2_b32 v98, v110, v111 offset0:96 offset1:132
	ds_write2_b32 v98, v112, v113 offset0:168 offset1:204
	v_lshlrev_b32_e32 v98, 2, v0
	v_and_b32_e32 v102, 28, v98
	v_lshlrev_b32_e32 v108, 2, v102
	v_lshlrev_b32_e32 v102, 1, v102
	v_mov_b32_e32 v103, v1
	v_bfe_u32 v131, v0, 3, 3
	v_ashrrev_i32_e32 v127, 31, v126
	v_mov_b32_e32 v109, v1
	v_lshl_add_u64 v[104:105], v[118:119], 0, v[102:103]
	v_lshlrev_b32_e32 v110, 11, v131
	v_mov_b32_e32 v111, v1
	s_waitcnt lgkmcnt(0)
	v_lshl_add_u64 v[100:101], v[120:121], 0, v[108:109]
	v_lshlrev_b64 v[98:99], 2, v[126:127]
	v_mul_u32_u24_e32 v0, 0x90, v131
	v_lshl_add_u64 v[110:111], v[104:105], 0, v[110:111]
	v_lshl_add_u64 v[100:101], v[100:101], 0, v[98:99]
	v_lshl_add_u64 v[106:107], v[124:125], 0, v[108:109]
	v_lshl_add_u64 v[102:103], v[122:123], 0, v[108:109]
	v_add3_u32 v0, v151, v108, v0
	v_lshlrev_b32_e32 v108, 12, v131
	global_load_dwordx4 v[180:183], v[100:101], off
	v_mov_b32_e32 v212, v131
	v_lshlrev_b32_e32 v184, 11, v212
	v_mov_b32_e32 v185, v1
	v_lshl_add_u64 v[184:185], v[104:105], 0, v[184:185]
	global_load_dwordx2 v[184:185], v[184:185], off offset:64
	v_lshlrev_b32_e32 v192, 12, v212
	v_mov_b32_e32 v193, v1
	v_lshl_add_u64 v[192:193], v[106:107], 0, v[192:193]
	global_load_dwordx4 v[192:195], v[192:193], off offset:128
	v_or_b32_e32 v212, 8, v131
	v_lshlrev_b32_e32 v186, 11, v212
	v_mov_b32_e32 v187, v1
	v_lshl_add_u64 v[186:187], v[104:105], 0, v[186:187]
	global_load_dwordx2 v[186:187], v[186:187], off offset:64
	v_lshlrev_b32_e32 v200, 12, v212
	v_mov_b32_e32 v201, v1
	v_lshl_add_u64 v[200:201], v[106:107], 0, v[200:201]
	global_load_dwordx4 v[200:203], v[200:201], off offset:128
	v_or_b32_e32 v212, 16, v131
	v_lshlrev_b32_e32 v188, 11, v212
	v_mov_b32_e32 v189, v1
	v_lshl_add_u64 v[188:189], v[104:105], 0, v[188:189]
	global_load_dwordx2 v[188:189], v[188:189], off offset:64
	v_lshlrev_b32_e32 v204, 12, v212
	v_mov_b32_e32 v205, v1
	v_lshl_add_u64 v[204:205], v[106:107], 0, v[204:205]
	global_load_dwordx4 v[204:207], v[204:205], off offset:128
	v_or_b32_e32 v212, 24, v131
	v_lshlrev_b32_e32 v190, 11, v212
	v_mov_b32_e32 v191, v1
	v_lshl_add_u64 v[190:191], v[104:105], 0, v[190:191]
	global_load_dwordx2 v[190:191], v[190:191], off offset:64
	v_lshlrev_b32_e32 v208, 12, v212
	v_mov_b32_e32 v209, v1
	v_lshl_add_u64 v[208:209], v[106:107], 0, v[208:209]
	global_load_dwordx4 v[208:211], v[208:209], off offset:128
	s_waitcnt vmcnt(6)
	v_mov_b32_e32 v126, v184
	v_mov_b32_e32 v127, v185
	v_lshl_add_u64 v[112:113], v[106:107], 0, v[108:109]
	v_lshl_add_u64 v[128:129], v[102:103], 0, v[108:109]
	ds_read_b128 v[108:111], v0
	v_mov_b32_e32 v118, v180
	v_mov_b32_e32 v119, v181
	v_mov_b32_e32 v120, v182
	v_mov_b32_e32 v121, v183
	v_mov_b32_e32 v122, v192
	v_mov_b32_e32 v123, v193
	v_mov_b32_e32 v124, v194
	v_mov_b32_e32 v125, v195
	v_and_b32_e32 v113, 0xffff0000, v126
	v_lshlrev_b32_e32 v112, 16, v126
	v_pk_add_f32 v[112:113], v[122:123], v[112:113]
	s_waitcnt lgkmcnt(0)
	v_pk_fma_f32 v[108:109], v[108:109], v[118:119], v[112:113]
	v_and_b32_e32 v113, 0xffff0000, v127
	v_lshlrev_b32_e32 v112, 16, v127
	v_pk_add_f32 v[112:113], v[124:125], v[112:113]
	s_nop 0
	v_pk_fma_f32 v[110:111], v[110:111], v[120:121], v[112:113]
	global_store_dwordx4 v[128:129], v[108:111], off offset:128
	s_nop 1
	v_or_b32_e32 v110, 8, v131
	v_lshlrev_b32_e32 v108, 12, v110
	v_lshlrev_b32_e32 v110, 11, v110
	v_mov_b32_e32 v111, v1
	v_lshl_add_u64 v[110:111], v[104:105], 0, v[110:111]
	v_mov_b32_e32 v109, v1
	s_waitcnt vmcnt(5)
	v_mov_b32_e32 v126, v186
	v_mov_b32_e32 v127, v187
	v_lshl_add_u64 v[112:113], v[106:107], 0, v[108:109]
	v_lshl_add_u64 v[128:129], v[102:103], 0, v[108:109]
	ds_read_b128 v[108:111], v0 offset:1152
	v_mov_b32_e32 v118, v180
	v_mov_b32_e32 v119, v181
	v_mov_b32_e32 v120, v182
	v_mov_b32_e32 v121, v183
	v_mov_b32_e32 v122, v200
	v_mov_b32_e32 v123, v201
	v_mov_b32_e32 v124, v202
	v_mov_b32_e32 v125, v203
	v_and_b32_e32 v113, 0xffff0000, v126
	v_lshlrev_b32_e32 v112, 16, v126
	v_pk_add_f32 v[112:113], v[122:123], v[112:113]
	s_waitcnt lgkmcnt(0)
	v_pk_fma_f32 v[108:109], v[108:109], v[118:119], v[112:113]
	v_and_b32_e32 v113, 0xffff0000, v127
	v_lshlrev_b32_e32 v112, 16, v127
	v_pk_add_f32 v[112:113], v[124:125], v[112:113]
	s_nop 0
	v_pk_fma_f32 v[110:111], v[110:111], v[120:121], v[112:113]
	global_store_dwordx4 v[128:129], v[108:111], off offset:128
	s_nop 1
	v_or_b32_e32 v110, 16, v131
	v_lshlrev_b32_e32 v108, 12, v110
	v_lshlrev_b32_e32 v110, 11, v110
	v_mov_b32_e32 v111, v1
	v_lshl_add_u64 v[110:111], v[104:105], 0, v[110:111]
	v_mov_b32_e32 v109, v1
	s_waitcnt vmcnt(4)
	v_mov_b32_e32 v126, v188
	v_mov_b32_e32 v127, v189
	v_lshl_add_u64 v[112:113], v[106:107], 0, v[108:109]
	v_lshl_add_u64 v[128:129], v[102:103], 0, v[108:109]
	ds_read_b128 v[108:111], v0 offset:2304
	v_mov_b32_e32 v118, v180
	v_mov_b32_e32 v119, v181
	v_mov_b32_e32 v120, v182
	v_mov_b32_e32 v121, v183
	v_mov_b32_e32 v122, v204
	v_mov_b32_e32 v123, v205
	v_mov_b32_e32 v124, v206
	v_mov_b32_e32 v125, v207
	v_and_b32_e32 v113, 0xffff0000, v126
	v_lshlrev_b32_e32 v112, 16, v126
	v_pk_add_f32 v[112:113], v[122:123], v[112:113]
	s_waitcnt lgkmcnt(0)
	v_pk_fma_f32 v[108:109], v[108:109], v[118:119], v[112:113]
	v_and_b32_e32 v113, 0xffff0000, v127
	v_lshlrev_b32_e32 v112, 16, v127
	v_pk_add_f32 v[112:113], v[124:125], v[112:113]
	s_nop 0
	v_pk_fma_f32 v[110:111], v[110:111], v[120:121], v[112:113]
	v_or_b32_e32 v112, 24, v131
	global_store_dwordx4 v[128:129], v[108:111], off offset:128
	s_nop 1
	v_lshlrev_b32_e32 v108, 12, v112
	v_mov_b32_e32 v109, v1
	v_lshl_add_u64 v[110:111], v[106:107], 0, v[108:109]
	v_lshlrev_b32_e32 v106, 11, v112
	v_mov_b32_e32 v107, v1
	v_lshl_add_u64 v[104:105], v[104:105], 0, v[106:107]
	s_waitcnt vmcnt(3)
	v_mov_b32_e32 v118, v190
	v_mov_b32_e32 v119, v191
	v_lshl_add_u64 v[120:121], v[102:103], 0, v[108:109]
	ds_read_b128 v[102:105], v0 offset:3456
	v_mov_b32_e32 v106, v180
	v_mov_b32_e32 v107, v181
	v_mov_b32_e32 v108, v182
	v_mov_b32_e32 v109, v183
	s_nop 0
	v_mov_b32_e32 v110, v208
	v_mov_b32_e32 v111, v209
	v_mov_b32_e32 v112, v210
	v_mov_b32_e32 v113, v211
	v_and_b32_e32 v101, 0xffff0000, v118
	v_lshlrev_b32_e32 v100, 16, v118
	v_pk_add_f32 v[100:101], v[110:111], v[100:101]
	s_waitcnt lgkmcnt(0)
	v_pk_fma_f32 v[100:101], v[102:103], v[106:107], v[100:101]
	v_and_b32_e32 v103, 0xffff0000, v119
	v_lshlrev_b32_e32 v102, 16, v119
	v_pk_add_f32 v[102:103], v[112:113], v[102:103]
	s_nop 0
	v_pk_fma_f32 v[102:103], v[104:105], v[108:109], v[102:103]
	global_store_dwordx4 v[120:121], v[100:103], off offset:128
	s_nop 1
	v_or_b32_e32 v100, 32, v130
	v_add_u32_e32 v0, v100, v155
	v_ashrrev_i32_e32 v0, 14, v0
	v_mul_i32_i24_e32 v101, 0x4000, v0
	v_sub_u32_e32 v101, v100, v101
	v_add_u32_e32 v106, 0x100, v101
	v_mul_i32_i24_e32 v102, 0xc00, v0
	v_mul_hi_i32_i24_e32 v105, 0x4100, v0
	v_mul_i32_i24_e32 v104, 0x4100, v0
	v_ashrrev_i32_e32 v107, 31, v106
	v_mov_b32_e32 v0, v179
	v_lshl_add_u64 v[104:105], v[104:105], 0, v[106:107]
	v_ashrrev_i32_e32 v103, 31, v102
	v_and_b32_e32 v106, 31, v0
	v_bfe_u32 v107, v0, 5, 1
	v_mul_u32_u24_e32 v107, 0x240, v107
	v_lshlrev_b32_e32 v106, 2, v106
	v_add3_u32 v106, v151, v107, v106
	ds_write2_b32 v106, v82, v83 offset1:36
	ds_write2_b32 v106, v84, v85 offset0:72 offset1:108
	v_add_u32_e32 v82, 0x400, v106
	ds_write2_b32 v82, v86, v87 offset0:32 offset1:68
	ds_write2_b32 v82, v88, v89 offset0:104 offset1:140
	v_add_u32_e32 v82, 0x800, v106
	ds_write2_b32 v82, v90, v91 offset0:64 offset1:100
	ds_write2_b32 v82, v92, v93 offset0:136 offset1:172
	v_add_u32_e32 v82, 0xc00, v106
	v_lshlrev_b64 v[104:105], 11, v[104:105]
	v_ashrrev_i32_e32 v101, 31, v100
	ds_write2_b32 v82, v94, v95 offset0:96 offset1:132
	ds_write2_b32 v82, v96, v97 offset0:168 offset1:204
	v_lshl_add_u64 v[82:83], v[102:103], 2, s[54:55]
	v_lshlrev_b32_e32 v92, 2, v0
	v_lshl_add_u64 v[86:87], v[82:83], 0, s[2:3]
	v_lshl_add_u64 v[82:83], s[0:1], 0, v[104:105]
	v_lshlrev_b64 v[84:85], 12, v[100:101]
	v_and_b32_e32 v92, 28, v92
	v_lshl_add_u64 v[82:83], v[82:83], 0, v[116:117]
	v_lshl_add_u64 v[88:89], s[36:37], 0, v[84:85]
	v_lshl_add_u64 v[84:85], s[52:53], 0, v[84:85]
	v_lshlrev_b32_e32 v100, 2, v92
	v_lshlrev_b32_e32 v92, 1, v92
	v_mov_b32_e32 v93, v1
	v_bfe_u32 v122, v0, 3, 3
	v_lshl_add_u64 v[90:91], v[86:87], 0, v[114:115]
	v_lshl_add_u64 v[88:89], v[88:89], 0, v[114:115]
	v_lshl_add_u64 v[84:85], v[84:85], 0, v[114:115]
	v_mov_b32_e32 v101, v1
	v_lshl_add_u64 v[94:95], v[82:83], 0, v[92:93]
	v_mul_u32_u24_e32 v0, 0x90, v122
	v_lshlrev_b32_e32 v102, 11, v122
	v_mov_b32_e32 v103, v1
	s_waitcnt lgkmcnt(0)
	v_lshl_add_u64 v[90:91], v[90:91], 0, v[100:101]
	v_lshl_add_u64 v[96:97], v[88:89], 0, v[100:101]
	v_lshl_add_u64 v[92:93], v[84:85], 0, v[100:101]
	v_add3_u32 v0, v151, v100, v0
	v_lshlrev_b32_e32 v100, 12, v122
	v_lshl_add_u64 v[102:103], v[94:95], 0, v[102:103]
	v_lshl_add_u64 v[108:109], v[96:97], 0, v[100:101]
	global_load_dwordx4 v[180:183], v[90:91], off
	v_mov_b32_e32 v212, v122
	v_lshlrev_b32_e32 v184, 11, v212
	v_mov_b32_e32 v185, v1
	v_lshl_add_u64 v[184:185], v[94:95], 0, v[184:185]
	global_load_dwordx2 v[184:185], v[184:185], off
	v_lshlrev_b32_e32 v192, 12, v212
	v_mov_b32_e32 v193, v1
	v_lshl_add_u64 v[192:193], v[96:97], 0, v[192:193]
	global_load_dwordx4 v[192:195], v[192:193], off
	v_or_b32_e32 v212, 8, v122
	v_lshlrev_b32_e32 v186, 11, v212
	v_mov_b32_e32 v187, v1
	v_lshl_add_u64 v[186:187], v[94:95], 0, v[186:187]
	global_load_dwordx2 v[186:187], v[186:187], off
	v_lshlrev_b32_e32 v200, 12, v212
	v_mov_b32_e32 v201, v1
	v_lshl_add_u64 v[200:201], v[96:97], 0, v[200:201]
	global_load_dwordx4 v[200:203], v[200:201], off
	v_or_b32_e32 v212, 16, v122
	v_lshlrev_b32_e32 v188, 11, v212
	v_mov_b32_e32 v189, v1
	v_lshl_add_u64 v[188:189], v[94:95], 0, v[188:189]
	global_load_dwordx2 v[188:189], v[188:189], off
	v_lshlrev_b32_e32 v204, 12, v212
	v_mov_b32_e32 v205, v1
	v_lshl_add_u64 v[204:205], v[96:97], 0, v[204:205]
	global_load_dwordx4 v[204:207], v[204:205], off
	v_or_b32_e32 v212, 24, v122
	v_lshlrev_b32_e32 v190, 11, v212
	v_mov_b32_e32 v191, v1
	v_lshl_add_u64 v[190:191], v[94:95], 0, v[190:191]
	global_load_dwordx2 v[190:191], v[190:191], off
	v_lshlrev_b32_e32 v208, 12, v212
	v_mov_b32_e32 v209, v1
	v_lshl_add_u64 v[208:209], v[96:97], 0, v[208:209]
	global_load_dwordx4 v[208:211], v[208:209], off
	s_waitcnt vmcnt(6)
	v_mov_b32_e32 v112, v184
	v_mov_b32_e32 v113, v185
	v_lshl_add_u64 v[118:119], v[92:93], 0, v[100:101]
	ds_read_b128 v[100:103], v0
	v_mov_b32_e32 v104, v180
	v_mov_b32_e32 v105, v181
	v_mov_b32_e32 v106, v182
	v_mov_b32_e32 v107, v183
	s_nop 0
	v_mov_b32_e32 v108, v192
	v_mov_b32_e32 v109, v193
	v_mov_b32_e32 v110, v194
	v_mov_b32_e32 v111, v195
	v_and_b32_e32 v121, 0xffff0000, v112
	v_lshlrev_b32_e32 v120, 16, v112
	v_pk_add_f32 v[108:109], v[108:109], v[120:121]
	s_waitcnt lgkmcnt(0)
	v_pk_fma_f32 v[100:101], v[100:101], v[104:105], v[108:109]
	v_and_b32_e32 v105, 0xffff0000, v113
	v_lshlrev_b32_e32 v104, 16, v113
	v_pk_add_f32 v[104:105], v[110:111], v[104:105]
	s_nop 0
	v_pk_fma_f32 v[102:103], v[102:103], v[106:107], v[104:105]
	global_store_dwordx4 v[118:119], v[100:103], off
	s_nop 1
	v_or_b32_e32 v102, 8, v122
	v_lshlrev_b32_e32 v100, 12, v102
	v_lshlrev_b32_e32 v102, 11, v102
	v_mov_b32_e32 v103, v1
	v_mov_b32_e32 v101, v1
	v_lshl_add_u64 v[102:103], v[94:95], 0, v[102:103]
	v_lshl_add_u64 v[108:109], v[96:97], 0, v[100:101]
	s_waitcnt vmcnt(5)
	v_mov_b32_e32 v112, v186
	v_mov_b32_e32 v113, v187
	v_lshl_add_u64 v[118:119], v[92:93], 0, v[100:101]
	ds_read_b128 v[100:103], v0 offset:1152
	v_mov_b32_e32 v104, v180
	v_mov_b32_e32 v105, v181
	v_mov_b32_e32 v106, v182
	v_mov_b32_e32 v107, v183
	s_nop 0
	v_mov_b32_e32 v108, v200
	v_mov_b32_e32 v109, v201
	v_mov_b32_e32 v110, v202
	v_mov_b32_e32 v111, v203
	v_and_b32_e32 v121, 0xffff0000, v112
	v_lshlrev_b32_e32 v120, 16, v112
	v_pk_add_f32 v[108:109], v[108:109], v[120:121]
	s_waitcnt lgkmcnt(0)
	v_pk_fma_f32 v[100:101], v[100:101], v[104:105], v[108:109]
	v_and_b32_e32 v105, 0xffff0000, v113
	v_lshlrev_b32_e32 v104, 16, v113
	v_pk_add_f32 v[104:105], v[110:111], v[104:105]
	s_nop 0
	v_pk_fma_f32 v[102:103], v[102:103], v[106:107], v[104:105]
	global_store_dwordx4 v[118:119], v[100:103], off
	s_nop 1
	v_or_b32_e32 v102, 16, v122
	v_lshlrev_b32_e32 v100, 12, v102
	v_lshlrev_b32_e32 v102, 11, v102
	v_mov_b32_e32 v103, v1
	v_mov_b32_e32 v101, v1
	v_lshl_add_u64 v[102:103], v[94:95], 0, v[102:103]
	v_lshl_add_u64 v[108:109], v[96:97], 0, v[100:101]
	s_waitcnt vmcnt(4)
	v_mov_b32_e32 v112, v188
	v_mov_b32_e32 v113, v189
	v_lshl_add_u64 v[118:119], v[92:93], 0, v[100:101]
	ds_read_b128 v[100:103], v0 offset:2304
	v_mov_b32_e32 v104, v180
	v_mov_b32_e32 v105, v181
	v_mov_b32_e32 v106, v182
	v_mov_b32_e32 v107, v183
	s_nop 0
	v_mov_b32_e32 v108, v204
	v_mov_b32_e32 v109, v205
	v_mov_b32_e32 v110, v206
	v_mov_b32_e32 v111, v207
	v_and_b32_e32 v121, 0xffff0000, v112
	v_lshlrev_b32_e32 v120, 16, v112
	v_pk_add_f32 v[108:109], v[108:109], v[120:121]
	s_waitcnt lgkmcnt(0)
	v_pk_fma_f32 v[100:101], v[100:101], v[104:105], v[108:109]
	v_and_b32_e32 v105, 0xffff0000, v113
	v_lshlrev_b32_e32 v104, 16, v113
	v_pk_add_f32 v[104:105], v[110:111], v[104:105]
	s_nop 0
	v_pk_fma_f32 v[102:103], v[102:103], v[106:107], v[104:105]
	global_store_dwordx4 v[118:119], v[100:103], off
	s_nop 1
	v_or_b32_e32 v102, 24, v122
	v_lshlrev_b32_e32 v100, 12, v102
	v_lshlrev_b32_e32 v102, 11, v102
	v_mov_b32_e32 v103, v1
	v_lshl_add_u64 v[94:95], v[94:95], 0, v[102:103]
	v_mov_b32_e32 v101, v1
	s_waitcnt vmcnt(3)
	v_mov_b32_e32 v108, v190
	v_mov_b32_e32 v109, v191
	v_lshl_add_u64 v[96:97], v[96:97], 0, v[100:101]
	v_lshl_add_u64 v[110:111], v[92:93], 0, v[100:101]
	ds_read_b128 v[92:95], v0 offset:3456
	v_mov_b32_e32 v100, v180
	v_mov_b32_e32 v101, v181
	v_mov_b32_e32 v102, v182
	v_mov_b32_e32 v103, v183
	v_mov_b32_e32 v104, v208
	v_mov_b32_e32 v105, v209
	v_mov_b32_e32 v106, v210
	v_mov_b32_e32 v107, v211
	v_and_b32_e32 v91, 0xffff0000, v108
	v_lshlrev_b32_e32 v90, 16, v108
	v_pk_add_f32 v[90:91], v[104:105], v[90:91]
	s_waitcnt lgkmcnt(0)
	v_pk_fma_f32 v[90:91], v[92:93], v[100:101], v[90:91]
	v_and_b32_e32 v93, 0xffff0000, v109
	v_lshlrev_b32_e32 v92, 16, v109
	v_pk_add_f32 v[92:93], v[106:107], v[92:93]
	s_nop 0
	v_pk_fma_f32 v[92:93], v[94:95], v[102:103], v[92:93]
	global_store_dwordx4 v[110:111], v[90:93], off
	v_mov_b32_e32 v0, v179
	s_nop 0
	v_and_b32_e32 v90, 31, v0
	v_bfe_u32 v91, v0, 5, 1
	v_mul_u32_u24_e32 v91, 0x240, v91
	v_lshlrev_b32_e32 v90, 2, v90
	v_add3_u32 v90, v151, v91, v90
	ds_write2_b32 v90, v66, v67 offset1:36
	ds_write2_b32 v90, v68, v69 offset0:72 offset1:108
	v_add_u32_e32 v66, 0x400, v90
	ds_write2_b32 v66, v70, v71 offset0:32 offset1:68
	ds_write2_b32 v66, v72, v73 offset0:104 offset1:140
	v_add_u32_e32 v66, 0x800, v90
	ds_write2_b32 v66, v74, v75 offset0:64 offset1:100
	ds_write2_b32 v66, v76, v77 offset0:136 offset1:172
	v_add_u32_e32 v66, 0xc00, v90
	ds_write2_b32 v66, v78, v79 offset0:96 offset1:132
	ds_write2_b32 v66, v80, v81 offset0:168 offset1:204
	v_lshlrev_b32_e32 v66, 2, v0
	v_and_b32_e32 v68, 28, v66
	v_lshlrev_b32_e32 v74, 2, v68
	v_lshlrev_b32_e32 v68, 1, v68
	v_mov_b32_e32 v69, v1
	v_bfe_u32 v92, v0, 3, 3
	v_mov_b32_e32 v75, v1
	v_lshl_add_u64 v[70:71], v[82:83], 0, v[68:69]
	v_mul_u32_u24_e32 v0, 0x90, v92
	v_lshlrev_b32_e32 v76, 11, v92
	v_mov_b32_e32 v77, v1
	s_waitcnt lgkmcnt(0)
	v_lshl_add_u64 v[66:67], v[86:87], 0, v[74:75]
	v_lshl_add_u64 v[72:73], v[88:89], 0, v[74:75]
	v_lshl_add_u64 v[68:69], v[84:85], 0, v[74:75]
	v_add3_u32 v0, v151, v74, v0
	v_lshlrev_b32_e32 v74, 12, v92
	v_lshl_add_u64 v[76:77], v[70:71], 0, v[76:77]
	v_lshl_add_u64 v[66:67], v[66:67], 0, v[98:99]
	v_lshl_add_u64 v[82:83], v[72:73], 0, v[74:75]
	global_load_dwordx4 v[180:183], v[66:67], off
	v_mov_b32_e32 v212, v92
	v_lshlrev_b32_e32 v184, 11, v212
	v_mov_b32_e32 v185, v1
	v_lshl_add_u64 v[184:185], v[70:71], 0, v[184:185]
	global_load_dwordx2 v[184:185], v[184:185], off offset:64
	v_lshlrev_b32_e32 v192, 12, v212
	v_mov_b32_e32 v193, v1
	v_lshl_add_u64 v[192:193], v[72:73], 0, v[192:193]
	global_load_dwordx4 v[192:195], v[192:193], off offset:128
	v_or_b32_e32 v212, 8, v92
	v_lshlrev_b32_e32 v186, 11, v212
	v_mov_b32_e32 v187, v1
	v_lshl_add_u64 v[186:187], v[70:71], 0, v[186:187]
	global_load_dwordx2 v[186:187], v[186:187], off offset:64
	v_lshlrev_b32_e32 v200, 12, v212
	v_mov_b32_e32 v201, v1
	v_lshl_add_u64 v[200:201], v[72:73], 0, v[200:201]
	global_load_dwordx4 v[200:203], v[200:201], off offset:128
	v_or_b32_e32 v212, 16, v92
	v_lshlrev_b32_e32 v188, 11, v212
	v_mov_b32_e32 v189, v1
	v_lshl_add_u64 v[188:189], v[70:71], 0, v[188:189]
	global_load_dwordx2 v[188:189], v[188:189], off offset:64
	v_lshlrev_b32_e32 v204, 12, v212
	v_mov_b32_e32 v205, v1
	v_lshl_add_u64 v[204:205], v[72:73], 0, v[204:205]
	global_load_dwordx4 v[204:207], v[204:205], off offset:128
	v_or_b32_e32 v212, 24, v92
	v_lshlrev_b32_e32 v190, 11, v212
	v_mov_b32_e32 v191, v1
	v_lshl_add_u64 v[190:191], v[70:71], 0, v[190:191]
	global_load_dwordx2 v[190:191], v[190:191], off offset:64
	v_lshlrev_b32_e32 v208, 12, v212
	v_mov_b32_e32 v209, v1
	v_lshl_add_u64 v[208:209], v[72:73], 0, v[208:209]
	global_load_dwordx4 v[208:211], v[208:209], off offset:128
	s_waitcnt vmcnt(6)
	v_mov_b32_e32 v86, v184
	v_mov_b32_e32 v87, v185
	v_lshl_add_u64 v[88:89], v[68:69], 0, v[74:75]
	ds_read_b128 v[74:77], v0
	v_mov_b32_e32 v78, v180
	v_mov_b32_e32 v79, v181
	v_mov_b32_e32 v80, v182
	v_mov_b32_e32 v81, v183
	s_nop 0
	v_mov_b32_e32 v82, v192
	v_mov_b32_e32 v83, v193
	v_mov_b32_e32 v84, v194
	v_mov_b32_e32 v85, v195
	v_and_b32_e32 v91, 0xffff0000, v86
	v_lshlrev_b32_e32 v90, 16, v86
	v_pk_add_f32 v[82:83], v[82:83], v[90:91]
	s_waitcnt lgkmcnt(0)
	v_pk_fma_f32 v[74:75], v[74:75], v[78:79], v[82:83]
	v_and_b32_e32 v79, 0xffff0000, v87
	v_lshlrev_b32_e32 v78, 16, v87
	v_pk_add_f32 v[78:79], v[84:85], v[78:79]
	s_nop 0
	v_pk_fma_f32 v[76:77], v[76:77], v[80:81], v[78:79]
	global_store_dwordx4 v[88:89], v[74:77], off offset:128
	s_nop 1
	v_or_b32_e32 v76, 8, v92
	v_lshlrev_b32_e32 v74, 12, v76
	v_lshlrev_b32_e32 v76, 11, v76
	v_mov_b32_e32 v77, v1
	v_mov_b32_e32 v75, v1
	v_lshl_add_u64 v[76:77], v[70:71], 0, v[76:77]
	v_lshl_add_u64 v[82:83], v[72:73], 0, v[74:75]
	s_waitcnt vmcnt(5)
	v_mov_b32_e32 v86, v186
	v_mov_b32_e32 v87, v187
	v_lshl_add_u64 v[88:89], v[68:69], 0, v[74:75]
	ds_read_b128 v[74:77], v0 offset:1152
	v_mov_b32_e32 v78, v180
	v_mov_b32_e32 v79, v181
	v_mov_b32_e32 v80, v182
	v_mov_b32_e32 v81, v183
	s_nop 0
	v_mov_b32_e32 v82, v200
	v_mov_b32_e32 v83, v201
	v_mov_b32_e32 v84, v202
	v_mov_b32_e32 v85, v203
	v_and_b32_e32 v91, 0xffff0000, v86
	v_lshlrev_b32_e32 v90, 16, v86
	v_pk_add_f32 v[82:83], v[82:83], v[90:91]
	s_waitcnt lgkmcnt(0)
	v_pk_fma_f32 v[74:75], v[74:75], v[78:79], v[82:83]
	v_and_b32_e32 v79, 0xffff0000, v87
	v_lshlrev_b32_e32 v78, 16, v87
	v_pk_add_f32 v[78:79], v[84:85], v[78:79]
	s_nop 0
	v_pk_fma_f32 v[76:77], v[76:77], v[80:81], v[78:79]
	global_store_dwordx4 v[88:89], v[74:77], off offset:128
	s_nop 1
	v_or_b32_e32 v76, 16, v92
	v_lshlrev_b32_e32 v74, 12, v76
	v_lshlrev_b32_e32 v76, 11, v76
	v_mov_b32_e32 v77, v1
	v_mov_b32_e32 v75, v1
	v_lshl_add_u64 v[76:77], v[70:71], 0, v[76:77]
	v_lshl_add_u64 v[82:83], v[72:73], 0, v[74:75]
	s_waitcnt vmcnt(4)
	v_mov_b32_e32 v86, v188
	v_mov_b32_e32 v87, v189
	v_lshl_add_u64 v[88:89], v[68:69], 0, v[74:75]
	ds_read_b128 v[74:77], v0 offset:2304
	v_mov_b32_e32 v78, v180
	v_mov_b32_e32 v79, v181
	v_mov_b32_e32 v80, v182
	v_mov_b32_e32 v81, v183
	s_nop 0
	v_mov_b32_e32 v82, v204
	v_mov_b32_e32 v83, v205
	v_mov_b32_e32 v84, v206
	v_mov_b32_e32 v85, v207
	v_and_b32_e32 v91, 0xffff0000, v86
	v_lshlrev_b32_e32 v90, 16, v86
	v_pk_add_f32 v[82:83], v[82:83], v[90:91]
	s_waitcnt lgkmcnt(0)
	v_pk_fma_f32 v[74:75], v[74:75], v[78:79], v[82:83]
	v_and_b32_e32 v79, 0xffff0000, v87
	v_lshlrev_b32_e32 v78, 16, v87
	v_pk_add_f32 v[78:79], v[84:85], v[78:79]
	s_nop 0
	v_pk_fma_f32 v[76:77], v[76:77], v[80:81], v[78:79]
	v_or_b32_e32 v78, 24, v92
	global_store_dwordx4 v[88:89], v[74:77], off offset:128
	s_nop 1
	v_lshlrev_b32_e32 v74, 12, v78
	v_mov_b32_e32 v75, v1
	v_lshl_add_u64 v[76:77], v[72:73], 0, v[74:75]
	v_lshlrev_b32_e32 v72, 11, v78
	v_mov_b32_e32 v73, v1
	v_lshl_add_u64 v[70:71], v[70:71], 0, v[72:73]
	s_waitcnt vmcnt(3)
	v_mov_b32_e32 v80, v190
	v_mov_b32_e32 v81, v191
	v_lshl_add_u64 v[82:83], v[68:69], 0, v[74:75]
	ds_read_b128 v[68:71], v0 offset:3456
	v_mov_b32_e32 v72, v180
	v_mov_b32_e32 v73, v181
	v_mov_b32_e32 v74, v182
	v_mov_b32_e32 v75, v183
	s_nop 0
	v_mov_b32_e32 v76, v208
	v_mov_b32_e32 v77, v209
	v_mov_b32_e32 v78, v210
	v_mov_b32_e32 v79, v211
	v_and_b32_e32 v67, 0xffff0000, v80
	v_lshlrev_b32_e32 v66, 16, v80
	v_pk_add_f32 v[66:67], v[76:77], v[66:67]
	s_waitcnt lgkmcnt(0)
	v_pk_fma_f32 v[66:67], v[68:69], v[72:73], v[66:67]
	v_and_b32_e32 v69, 0xffff0000, v81
	v_lshlrev_b32_e32 v68, 16, v81
	v_pk_add_f32 v[68:69], v[78:79], v[68:69]
	s_nop 0
	v_pk_fma_f32 v[68:69], v[70:71], v[74:75], v[68:69]
	global_store_dwordx4 v[82:83], v[66:69], off offset:128
	s_nop 1
	v_or_b32_e32 v66, 64, v130
	v_add_u32_e32 v0, v66, v155
	v_ashrrev_i32_e32 v0, 14, v0
	v_mul_i32_i24_e32 v67, 0x4000, v0
	v_sub_u32_e32 v67, v66, v67
	v_add_u32_e32 v72, 0x100, v67
	v_mul_i32_i24_e32 v68, 0xc00, v0
	v_mul_hi_i32_i24_e32 v71, 0x4100, v0
	v_mul_i32_i24_e32 v70, 0x4100, v0
	v_ashrrev_i32_e32 v73, 31, v72
	v_mov_b32_e32 v0, v179
	v_lshl_add_u64 v[70:71], v[70:71], 0, v[72:73]
	v_ashrrev_i32_e32 v69, 31, v68
	v_and_b32_e32 v72, 31, v0
	v_bfe_u32 v73, v0, 5, 1
	v_mul_u32_u24_e32 v73, 0x240, v73
	v_lshlrev_b32_e32 v72, 2, v72
	v_add3_u32 v72, v151, v73, v72
	ds_write2_b32 v72, v50, v51 offset1:36
	ds_write2_b32 v72, v52, v53 offset0:72 offset1:108
	v_add_u32_e32 v50, 0x400, v72
	ds_write2_b32 v50, v54, v55 offset0:32 offset1:68
	ds_write2_b32 v50, v56, v57 offset0:104 offset1:140
	v_add_u32_e32 v50, 0x800, v72
	ds_write2_b32 v50, v58, v59 offset0:64 offset1:100
	ds_write2_b32 v50, v60, v61 offset0:136 offset1:172
	v_add_u32_e32 v50, 0xc00, v72
	v_lshlrev_b64 v[70:71], 11, v[70:71]
	v_ashrrev_i32_e32 v67, 31, v66
	ds_write2_b32 v50, v62, v63 offset0:96 offset1:132
	ds_write2_b32 v50, v64, v65 offset0:168 offset1:204
	v_lshl_add_u64 v[50:51], v[68:69], 2, s[54:55]
	v_lshlrev_b32_e32 v60, 2, v0
	v_lshl_add_u64 v[54:55], v[50:51], 0, s[2:3]
	v_lshl_add_u64 v[50:51], s[0:1], 0, v[70:71]
	v_lshlrev_b64 v[52:53], 12, v[66:67]
	v_and_b32_e32 v60, 28, v60
	v_lshl_add_u64 v[50:51], v[50:51], 0, v[116:117]
	v_lshl_add_u64 v[56:57], s[36:37], 0, v[52:53]
	v_lshl_add_u64 v[52:53], s[52:53], 0, v[52:53]
	v_lshlrev_b32_e32 v66, 2, v60
	v_lshlrev_b32_e32 v60, 1, v60
	v_mov_b32_e32 v61, v1
	v_bfe_u32 v84, v0, 3, 3
	v_lshl_add_u64 v[58:59], v[54:55], 0, v[114:115]
	v_lshl_add_u64 v[56:57], v[56:57], 0, v[114:115]
	v_lshl_add_u64 v[52:53], v[52:53], 0, v[114:115]
	v_mov_b32_e32 v67, v1
	v_lshl_add_u64 v[62:63], v[50:51], 0, v[60:61]
	v_mul_u32_u24_e32 v0, 0x90, v84
	v_lshlrev_b32_e32 v68, 11, v84
	v_mov_b32_e32 v69, v1
	s_waitcnt lgkmcnt(0)
	v_lshl_add_u64 v[58:59], v[58:59], 0, v[66:67]
	v_lshl_add_u64 v[64:65], v[56:57], 0, v[66:67]
	v_lshl_add_u64 v[60:61], v[52:53], 0, v[66:67]
	v_add3_u32 v0, v151, v66, v0
	v_lshlrev_b32_e32 v66, 12, v84
	v_lshl_add_u64 v[68:69], v[62:63], 0, v[68:69]
	v_lshl_add_u64 v[74:75], v[64:65], 0, v[66:67]
	global_load_dwordx4 v[180:183], v[58:59], off
	v_mov_b32_e32 v212, v84
	v_lshlrev_b32_e32 v184, 11, v212
	v_mov_b32_e32 v185, v1
	v_lshl_add_u64 v[184:185], v[62:63], 0, v[184:185]
	global_load_dwordx2 v[184:185], v[184:185], off
	v_lshlrev_b32_e32 v192, 12, v212
	v_mov_b32_e32 v193, v1
	v_lshl_add_u64 v[192:193], v[64:65], 0, v[192:193]
	global_load_dwordx4 v[192:195], v[192:193], off
	v_or_b32_e32 v212, 8, v84
	v_lshlrev_b32_e32 v186, 11, v212
	v_mov_b32_e32 v187, v1
	v_lshl_add_u64 v[186:187], v[62:63], 0, v[186:187]
	global_load_dwordx2 v[186:187], v[186:187], off
	v_lshlrev_b32_e32 v200, 12, v212
	v_mov_b32_e32 v201, v1
	v_lshl_add_u64 v[200:201], v[64:65], 0, v[200:201]
	global_load_dwordx4 v[200:203], v[200:201], off
	v_or_b32_e32 v212, 16, v84
	v_lshlrev_b32_e32 v188, 11, v212
	v_mov_b32_e32 v189, v1
	v_lshl_add_u64 v[188:189], v[62:63], 0, v[188:189]
	global_load_dwordx2 v[188:189], v[188:189], off
	v_lshlrev_b32_e32 v204, 12, v212
	v_mov_b32_e32 v205, v1
	v_lshl_add_u64 v[204:205], v[64:65], 0, v[204:205]
	global_load_dwordx4 v[204:207], v[204:205], off
	v_or_b32_e32 v212, 24, v84
	v_lshlrev_b32_e32 v190, 11, v212
	v_mov_b32_e32 v191, v1
	v_lshl_add_u64 v[190:191], v[62:63], 0, v[190:191]
	global_load_dwordx2 v[190:191], v[190:191], off
	v_lshlrev_b32_e32 v208, 12, v212
	v_mov_b32_e32 v209, v1
	v_lshl_add_u64 v[208:209], v[64:65], 0, v[208:209]
	global_load_dwordx4 v[208:211], v[208:209], off
	s_waitcnt vmcnt(6)
	v_mov_b32_e32 v78, v184
	v_mov_b32_e32 v79, v185
	v_lshl_add_u64 v[80:81], v[60:61], 0, v[66:67]
	ds_read_b128 v[66:69], v0
	v_mov_b32_e32 v70, v180
	v_mov_b32_e32 v71, v181
	v_mov_b32_e32 v72, v182
	v_mov_b32_e32 v73, v183
	s_nop 0
	v_mov_b32_e32 v74, v192
	v_mov_b32_e32 v75, v193
	v_mov_b32_e32 v76, v194
	v_mov_b32_e32 v77, v195
	v_and_b32_e32 v83, 0xffff0000, v78
	v_lshlrev_b32_e32 v82, 16, v78
	v_pk_add_f32 v[74:75], v[74:75], v[82:83]
	s_waitcnt lgkmcnt(0)
	v_pk_fma_f32 v[66:67], v[66:67], v[70:71], v[74:75]
	v_and_b32_e32 v71, 0xffff0000, v79
	v_lshlrev_b32_e32 v70, 16, v79
	v_pk_add_f32 v[70:71], v[76:77], v[70:71]
	s_nop 0
	v_pk_fma_f32 v[68:69], v[68:69], v[72:73], v[70:71]
	global_store_dwordx4 v[80:81], v[66:69], off
	s_nop 1
	v_or_b32_e32 v68, 8, v84
	v_lshlrev_b32_e32 v66, 12, v68
	v_lshlrev_b32_e32 v68, 11, v68
	v_mov_b32_e32 v69, v1
	v_mov_b32_e32 v67, v1
	v_lshl_add_u64 v[68:69], v[62:63], 0, v[68:69]
	v_lshl_add_u64 v[74:75], v[64:65], 0, v[66:67]
	s_waitcnt vmcnt(5)
	v_mov_b32_e32 v78, v186
	v_mov_b32_e32 v79, v187
	v_lshl_add_u64 v[80:81], v[60:61], 0, v[66:67]
	ds_read_b128 v[66:69], v0 offset:1152
	v_mov_b32_e32 v70, v180
	v_mov_b32_e32 v71, v181
	v_mov_b32_e32 v72, v182
	v_mov_b32_e32 v73, v183
	s_nop 0
	v_mov_b32_e32 v74, v200
	v_mov_b32_e32 v75, v201
	v_mov_b32_e32 v76, v202
	v_mov_b32_e32 v77, v203
	v_and_b32_e32 v83, 0xffff0000, v78
	v_lshlrev_b32_e32 v82, 16, v78
	v_pk_add_f32 v[74:75], v[74:75], v[82:83]
	s_waitcnt lgkmcnt(0)
	v_pk_fma_f32 v[66:67], v[66:67], v[70:71], v[74:75]
	v_and_b32_e32 v71, 0xffff0000, v79
	v_lshlrev_b32_e32 v70, 16, v79
	v_pk_add_f32 v[70:71], v[76:77], v[70:71]
	s_nop 0
	v_pk_fma_f32 v[68:69], v[68:69], v[72:73], v[70:71]
	global_store_dwordx4 v[80:81], v[66:69], off
	s_nop 1
	v_or_b32_e32 v68, 16, v84
	v_lshlrev_b32_e32 v66, 12, v68
	v_lshlrev_b32_e32 v68, 11, v68
	v_mov_b32_e32 v69, v1
	v_mov_b32_e32 v67, v1
	v_lshl_add_u64 v[68:69], v[62:63], 0, v[68:69]
	v_lshl_add_u64 v[74:75], v[64:65], 0, v[66:67]
	s_waitcnt vmcnt(4)
	v_mov_b32_e32 v78, v188
	v_mov_b32_e32 v79, v189
	v_lshl_add_u64 v[80:81], v[60:61], 0, v[66:67]
	ds_read_b128 v[66:69], v0 offset:2304
	v_mov_b32_e32 v70, v180
	v_mov_b32_e32 v71, v181
	v_mov_b32_e32 v72, v182
	v_mov_b32_e32 v73, v183
	s_nop 0
	v_mov_b32_e32 v74, v204
	v_mov_b32_e32 v75, v205
	v_mov_b32_e32 v76, v206
	v_mov_b32_e32 v77, v207
	v_and_b32_e32 v83, 0xffff0000, v78
	v_lshlrev_b32_e32 v82, 16, v78
	v_pk_add_f32 v[74:75], v[74:75], v[82:83]
	s_waitcnt lgkmcnt(0)
	v_pk_fma_f32 v[66:67], v[66:67], v[70:71], v[74:75]
	v_and_b32_e32 v71, 0xffff0000, v79
	v_lshlrev_b32_e32 v70, 16, v79
	v_pk_add_f32 v[70:71], v[76:77], v[70:71]
	s_nop 0
	v_pk_fma_f32 v[68:69], v[68:69], v[72:73], v[70:71]
	v_or_b32_e32 v70, 24, v84
	global_store_dwordx4 v[80:81], v[66:69], off
	s_nop 1
	v_lshlrev_b32_e32 v66, 12, v70
	v_mov_b32_e32 v67, v1
	v_lshl_add_u64 v[68:69], v[64:65], 0, v[66:67]
	v_lshlrev_b32_e32 v64, 11, v70
	v_mov_b32_e32 v65, v1
	v_lshl_add_u64 v[62:63], v[62:63], 0, v[64:65]
	s_waitcnt vmcnt(3)
	v_mov_b32_e32 v72, v190
	v_mov_b32_e32 v73, v191
	v_lshl_add_u64 v[74:75], v[60:61], 0, v[66:67]
	ds_read_b128 v[60:63], v0 offset:3456
	v_mov_b32_e32 v64, v180
	v_mov_b32_e32 v65, v181
	v_mov_b32_e32 v66, v182
	v_mov_b32_e32 v67, v183
	s_nop 0
	v_mov_b32_e32 v68, v208
	v_mov_b32_e32 v69, v209
	v_mov_b32_e32 v70, v210
	v_mov_b32_e32 v71, v211
	v_and_b32_e32 v59, 0xffff0000, v72
	v_lshlrev_b32_e32 v58, 16, v72
	v_pk_add_f32 v[58:59], v[68:69], v[58:59]
	s_waitcnt lgkmcnt(0)
	v_pk_fma_f32 v[58:59], v[60:61], v[64:65], v[58:59]
	v_and_b32_e32 v61, 0xffff0000, v73
	v_lshlrev_b32_e32 v60, 16, v73
	v_pk_add_f32 v[60:61], v[70:71], v[60:61]
	s_nop 0
	v_pk_fma_f32 v[60:61], v[62:63], v[66:67], v[60:61]
	global_store_dwordx4 v[74:75], v[58:61], off
	v_mov_b32_e32 v0, v179
	s_nop 0
	v_and_b32_e32 v58, 31, v0
	v_bfe_u32 v59, v0, 5, 1
	v_mul_u32_u24_e32 v59, 0x240, v59
	v_lshlrev_b32_e32 v58, 2, v58
	v_add3_u32 v58, v151, v59, v58
	ds_write2_b32 v58, v34, v35 offset1:36
	ds_write2_b32 v58, v36, v37 offset0:72 offset1:108
	v_add_u32_e32 v34, 0x400, v58
	ds_write2_b32 v34, v38, v39 offset0:32 offset1:68
	ds_write2_b32 v34, v40, v41 offset0:104 offset1:140
	v_add_u32_e32 v34, 0x800, v58
	ds_write2_b32 v34, v42, v43 offset0:64 offset1:100
	ds_write2_b32 v34, v44, v45 offset0:136 offset1:172
	v_add_u32_e32 v34, 0xc00, v58
	ds_write2_b32 v34, v46, v47 offset0:96 offset1:132
	ds_write2_b32 v34, v48, v49 offset0:168 offset1:204
	v_lshlrev_b32_e32 v34, 2, v0
	v_and_b32_e32 v36, 28, v34
	v_lshlrev_b32_e32 v42, 2, v36
	v_lshlrev_b32_e32 v36, 1, v36
	v_mov_b32_e32 v37, v1
	v_bfe_u32 v60, v0, 3, 3
	v_mov_b32_e32 v43, v1
	v_lshl_add_u64 v[38:39], v[50:51], 0, v[36:37]
	v_mul_u32_u24_e32 v0, 0x90, v60
	v_lshlrev_b32_e32 v44, 11, v60
	v_mov_b32_e32 v45, v1
	s_waitcnt lgkmcnt(0)
	v_lshl_add_u64 v[34:35], v[54:55], 0, v[42:43]
	v_lshl_add_u64 v[40:41], v[56:57], 0, v[42:43]
	v_lshl_add_u64 v[36:37], v[52:53], 0, v[42:43]
	v_add3_u32 v0, v151, v42, v0
	v_lshlrev_b32_e32 v42, 12, v60
	v_lshl_add_u64 v[44:45], v[38:39], 0, v[44:45]
	v_lshl_add_u64 v[34:35], v[34:35], 0, v[98:99]
	v_lshl_add_u64 v[50:51], v[40:41], 0, v[42:43]
	global_load_dwordx4 v[180:183], v[34:35], off
	v_mov_b32_e32 v212, v60
	v_lshlrev_b32_e32 v184, 11, v212
	v_mov_b32_e32 v185, v1
	v_lshl_add_u64 v[184:185], v[38:39], 0, v[184:185]
	global_load_dwordx2 v[184:185], v[184:185], off offset:64
	v_lshlrev_b32_e32 v192, 12, v212
	v_mov_b32_e32 v193, v1
	v_lshl_add_u64 v[192:193], v[40:41], 0, v[192:193]
	global_load_dwordx4 v[192:195], v[192:193], off offset:128
	v_or_b32_e32 v212, 8, v60
	v_lshlrev_b32_e32 v186, 11, v212
	v_mov_b32_e32 v187, v1
	v_lshl_add_u64 v[186:187], v[38:39], 0, v[186:187]
	global_load_dwordx2 v[186:187], v[186:187], off offset:64
	v_lshlrev_b32_e32 v200, 12, v212
	v_mov_b32_e32 v201, v1
	v_lshl_add_u64 v[200:201], v[40:41], 0, v[200:201]
	global_load_dwordx4 v[200:203], v[200:201], off offset:128
	v_or_b32_e32 v212, 16, v60
	v_lshlrev_b32_e32 v188, 11, v212
	v_mov_b32_e32 v189, v1
	v_lshl_add_u64 v[188:189], v[38:39], 0, v[188:189]
	global_load_dwordx2 v[188:189], v[188:189], off offset:64
	v_lshlrev_b32_e32 v204, 12, v212
	v_mov_b32_e32 v205, v1
	v_lshl_add_u64 v[204:205], v[40:41], 0, v[204:205]
	global_load_dwordx4 v[204:207], v[204:205], off offset:128
	v_or_b32_e32 v212, 24, v60
	v_lshlrev_b32_e32 v190, 11, v212
	v_mov_b32_e32 v191, v1
	v_lshl_add_u64 v[190:191], v[38:39], 0, v[190:191]
	global_load_dwordx2 v[190:191], v[190:191], off offset:64
	v_lshlrev_b32_e32 v208, 12, v212
	v_mov_b32_e32 v209, v1
	v_lshl_add_u64 v[208:209], v[40:41], 0, v[208:209]
	global_load_dwordx4 v[208:211], v[208:209], off offset:128
	s_waitcnt vmcnt(6)
	v_mov_b32_e32 v54, v184
	v_mov_b32_e32 v55, v185
	v_lshl_add_u64 v[56:57], v[36:37], 0, v[42:43]
	ds_read_b128 v[42:45], v0
	v_mov_b32_e32 v46, v180
	v_mov_b32_e32 v47, v181
	v_mov_b32_e32 v48, v182
	v_mov_b32_e32 v49, v183
	s_nop 0
	v_mov_b32_e32 v50, v192
	v_mov_b32_e32 v51, v193
	v_mov_b32_e32 v52, v194
	v_mov_b32_e32 v53, v195
	v_and_b32_e32 v59, 0xffff0000, v54
	v_lshlrev_b32_e32 v58, 16, v54
	v_pk_add_f32 v[50:51], v[50:51], v[58:59]
	s_waitcnt lgkmcnt(0)
	v_pk_fma_f32 v[42:43], v[42:43], v[46:47], v[50:51]
	v_and_b32_e32 v47, 0xffff0000, v55
	v_lshlrev_b32_e32 v46, 16, v55
	v_pk_add_f32 v[46:47], v[52:53], v[46:47]
	s_nop 0
	v_pk_fma_f32 v[44:45], v[44:45], v[48:49], v[46:47]
	global_store_dwordx4 v[56:57], v[42:45], off offset:128
	s_nop 1
	v_or_b32_e32 v44, 8, v60
	v_lshlrev_b32_e32 v42, 12, v44
	v_lshlrev_b32_e32 v44, 11, v44
	v_mov_b32_e32 v45, v1
	v_mov_b32_e32 v43, v1
	v_lshl_add_u64 v[44:45], v[38:39], 0, v[44:45]
	v_lshl_add_u64 v[50:51], v[40:41], 0, v[42:43]
	s_waitcnt vmcnt(5)
	v_mov_b32_e32 v54, v186
	v_mov_b32_e32 v55, v187
	v_lshl_add_u64 v[56:57], v[36:37], 0, v[42:43]
	ds_read_b128 v[42:45], v0 offset:1152
	v_mov_b32_e32 v46, v180
	v_mov_b32_e32 v47, v181
	v_mov_b32_e32 v48, v182
	v_mov_b32_e32 v49, v183
	s_nop 0
	v_mov_b32_e32 v50, v200
	v_mov_b32_e32 v51, v201
	v_mov_b32_e32 v52, v202
	v_mov_b32_e32 v53, v203
	v_and_b32_e32 v59, 0xffff0000, v54
	v_lshlrev_b32_e32 v58, 16, v54
	v_pk_add_f32 v[50:51], v[50:51], v[58:59]
	s_waitcnt lgkmcnt(0)
	v_pk_fma_f32 v[42:43], v[42:43], v[46:47], v[50:51]
	v_and_b32_e32 v47, 0xffff0000, v55
	v_lshlrev_b32_e32 v46, 16, v55
	v_pk_add_f32 v[46:47], v[52:53], v[46:47]
	s_nop 0
	v_pk_fma_f32 v[44:45], v[44:45], v[48:49], v[46:47]
	global_store_dwordx4 v[56:57], v[42:45], off offset:128
	s_nop 1
	v_or_b32_e32 v44, 16, v60
	v_lshlrev_b32_e32 v42, 12, v44
	v_lshlrev_b32_e32 v44, 11, v44
	v_mov_b32_e32 v45, v1
	v_mov_b32_e32 v43, v1
	v_lshl_add_u64 v[44:45], v[38:39], 0, v[44:45]
	v_lshl_add_u64 v[50:51], v[40:41], 0, v[42:43]
	s_waitcnt vmcnt(4)
	v_mov_b32_e32 v54, v188
	v_mov_b32_e32 v55, v189
	v_lshl_add_u64 v[56:57], v[36:37], 0, v[42:43]
	ds_read_b128 v[42:45], v0 offset:2304
	v_mov_b32_e32 v46, v180
	v_mov_b32_e32 v47, v181
	v_mov_b32_e32 v48, v182
	v_mov_b32_e32 v49, v183
	s_nop 0
	v_mov_b32_e32 v50, v204
	v_mov_b32_e32 v51, v205
	v_mov_b32_e32 v52, v206
	v_mov_b32_e32 v53, v207
	v_and_b32_e32 v59, 0xffff0000, v54
	v_lshlrev_b32_e32 v58, 16, v54
	v_pk_add_f32 v[50:51], v[50:51], v[58:59]
	s_waitcnt lgkmcnt(0)
	v_pk_fma_f32 v[42:43], v[42:43], v[46:47], v[50:51]
	v_and_b32_e32 v47, 0xffff0000, v55
	v_lshlrev_b32_e32 v46, 16, v55
	v_pk_add_f32 v[46:47], v[52:53], v[46:47]
	s_nop 0
	v_pk_fma_f32 v[44:45], v[44:45], v[48:49], v[46:47]
	v_or_b32_e32 v46, 24, v60
	global_store_dwordx4 v[56:57], v[42:45], off offset:128
	s_nop 1
	v_lshlrev_b32_e32 v42, 12, v46
	v_mov_b32_e32 v43, v1
	v_lshl_add_u64 v[44:45], v[40:41], 0, v[42:43]
	v_lshlrev_b32_e32 v40, 11, v46
	v_mov_b32_e32 v41, v1
	v_lshl_add_u64 v[38:39], v[38:39], 0, v[40:41]
	s_waitcnt vmcnt(3)
	v_mov_b32_e32 v48, v190
	v_mov_b32_e32 v49, v191
	v_lshl_add_u64 v[50:51], v[36:37], 0, v[42:43]
	ds_read_b128 v[36:39], v0 offset:3456
	v_mov_b32_e32 v40, v180
	v_mov_b32_e32 v41, v181
	v_mov_b32_e32 v42, v182
	v_mov_b32_e32 v43, v183
	s_nop 0
	v_mov_b32_e32 v44, v208
	v_mov_b32_e32 v45, v209
	v_mov_b32_e32 v46, v210
	v_mov_b32_e32 v47, v211
	v_and_b32_e32 v35, 0xffff0000, v48
	v_lshlrev_b32_e32 v34, 16, v48
	v_pk_add_f32 v[34:35], v[44:45], v[34:35]
	s_waitcnt lgkmcnt(0)
	v_pk_fma_f32 v[34:35], v[36:37], v[40:41], v[34:35]
	v_and_b32_e32 v37, 0xffff0000, v49
	v_lshlrev_b32_e32 v36, 16, v49
	v_pk_add_f32 v[36:37], v[46:47], v[36:37]
	s_nop 0
	v_pk_fma_f32 v[36:37], v[38:39], v[42:43], v[36:37]
	global_store_dwordx4 v[50:51], v[34:37], off offset:128
	s_nop 1
	v_or_b32_e32 v34, 0x60, v130
	v_add_u32_e32 v0, v34, v155
	v_ashrrev_i32_e32 v0, 14, v0
	v_mul_i32_i24_e32 v35, 0x4000, v0
	v_sub_u32_e32 v35, v34, v35
	v_add_u32_e32 v40, 0x100, v35
	v_mul_i32_i24_e32 v36, 0xc00, v0
	v_mul_hi_i32_i24_e32 v39, 0x4100, v0
	v_mul_i32_i24_e32 v38, 0x4100, v0
	v_ashrrev_i32_e32 v41, 31, v40
	v_mov_b32_e32 v0, v179
	v_lshl_add_u64 v[38:39], v[38:39], 0, v[40:41]
	v_ashrrev_i32_e32 v37, 31, v36
	v_and_b32_e32 v40, 31, v0
	v_bfe_u32 v41, v0, 5, 1
	v_mul_u32_u24_e32 v41, 0x240, v41
	v_lshlrev_b32_e32 v40, 2, v40
	v_add3_u32 v40, v151, v41, v40
	ds_write2_b32 v40, v18, v19 offset1:36
	ds_write2_b32 v40, v20, v21 offset0:72 offset1:108
	v_add_u32_e32 v18, 0x400, v40
	ds_write2_b32 v18, v22, v23 offset0:32 offset1:68
	ds_write2_b32 v18, v24, v25 offset0:104 offset1:140
	v_add_u32_e32 v18, 0x800, v40
	ds_write2_b32 v18, v26, v27 offset0:64 offset1:100
	ds_write2_b32 v18, v28, v29 offset0:136 offset1:172
	v_add_u32_e32 v18, 0xc00, v40
	v_lshlrev_b64 v[38:39], 11, v[38:39]
	v_ashrrev_i32_e32 v35, 31, v34
	ds_write2_b32 v18, v30, v31 offset0:96 offset1:132
	ds_write2_b32 v18, v32, v33 offset0:168 offset1:204
	v_lshl_add_u64 v[18:19], v[36:37], 2, s[54:55]
	v_lshlrev_b32_e32 v28, 2, v0
	v_lshl_add_u64 v[20:21], v[18:19], 0, s[2:3]
	v_lshl_add_u64 v[18:19], s[0:1], 0, v[38:39]
	v_lshlrev_b64 v[22:23], 12, v[34:35]
	v_and_b32_e32 v28, 28, v28
	v_lshl_add_u64 v[18:19], v[18:19], 0, v[116:117]
	v_lshl_add_u64 v[24:25], s[36:37], 0, v[22:23]
	v_lshl_add_u64 v[22:23], s[52:53], 0, v[22:23]
	v_lshlrev_b32_e32 v34, 2, v28
	v_lshlrev_b32_e32 v28, 1, v28
	v_mov_b32_e32 v29, v1
	v_bfe_u32 v52, v0, 3, 3
	v_lshl_add_u64 v[26:27], v[20:21], 0, v[114:115]
	v_lshl_add_u64 v[24:25], v[24:25], 0, v[114:115]
	v_lshl_add_u64 v[22:23], v[22:23], 0, v[114:115]
	v_mov_b32_e32 v35, v1
	v_lshl_add_u64 v[30:31], v[18:19], 0, v[28:29]
	v_mul_u32_u24_e32 v0, 0x90, v52
	v_lshlrev_b32_e32 v36, 11, v52
	v_mov_b32_e32 v37, v1
	s_waitcnt lgkmcnt(0)
	v_lshl_add_u64 v[26:27], v[26:27], 0, v[34:35]
	v_lshl_add_u64 v[32:33], v[24:25], 0, v[34:35]
	v_lshl_add_u64 v[28:29], v[22:23], 0, v[34:35]
	v_add3_u32 v0, v151, v34, v0
	v_lshlrev_b32_e32 v34, 12, v52
	v_lshl_add_u64 v[36:37], v[30:31], 0, v[36:37]
	v_lshl_add_u64 v[42:43], v[32:33], 0, v[34:35]
	global_load_dwordx4 v[180:183], v[26:27], off
	v_mov_b32_e32 v212, v52
	v_lshlrev_b32_e32 v184, 11, v212
	v_mov_b32_e32 v185, v1
	v_lshl_add_u64 v[184:185], v[30:31], 0, v[184:185]
	global_load_dwordx2 v[184:185], v[184:185], off
	v_lshlrev_b32_e32 v192, 12, v212
	v_mov_b32_e32 v193, v1
	v_lshl_add_u64 v[192:193], v[32:33], 0, v[192:193]
	global_load_dwordx4 v[192:195], v[192:193], off
	v_or_b32_e32 v212, 8, v52
	v_lshlrev_b32_e32 v186, 11, v212
	v_mov_b32_e32 v187, v1
	v_lshl_add_u64 v[186:187], v[30:31], 0, v[186:187]
	global_load_dwordx2 v[186:187], v[186:187], off
	v_lshlrev_b32_e32 v200, 12, v212
	v_mov_b32_e32 v201, v1
	v_lshl_add_u64 v[200:201], v[32:33], 0, v[200:201]
	global_load_dwordx4 v[200:203], v[200:201], off
	v_or_b32_e32 v212, 16, v52
	v_lshlrev_b32_e32 v188, 11, v212
	v_mov_b32_e32 v189, v1
	v_lshl_add_u64 v[188:189], v[30:31], 0, v[188:189]
	global_load_dwordx2 v[188:189], v[188:189], off
	v_lshlrev_b32_e32 v204, 12, v212
	v_mov_b32_e32 v205, v1
	v_lshl_add_u64 v[204:205], v[32:33], 0, v[204:205]
	global_load_dwordx4 v[204:207], v[204:205], off
	v_or_b32_e32 v212, 24, v52
	v_lshlrev_b32_e32 v190, 11, v212
	v_mov_b32_e32 v191, v1
	v_lshl_add_u64 v[190:191], v[30:31], 0, v[190:191]
	global_load_dwordx2 v[190:191], v[190:191], off
	v_lshlrev_b32_e32 v208, 12, v212
	v_mov_b32_e32 v209, v1
	v_lshl_add_u64 v[208:209], v[32:33], 0, v[208:209]
	global_load_dwordx4 v[208:211], v[208:209], off
	s_waitcnt vmcnt(6)
	v_mov_b32_e32 v46, v184
	v_mov_b32_e32 v47, v185
	v_lshl_add_u64 v[48:49], v[28:29], 0, v[34:35]
	ds_read_b128 v[34:37], v0
	v_mov_b32_e32 v38, v180
	v_mov_b32_e32 v39, v181
	v_mov_b32_e32 v40, v182
	v_mov_b32_e32 v41, v183
	s_nop 0
	v_mov_b32_e32 v42, v192
	v_mov_b32_e32 v43, v193
	v_mov_b32_e32 v44, v194
	v_mov_b32_e32 v45, v195
	v_and_b32_e32 v51, 0xffff0000, v46
	v_lshlrev_b32_e32 v50, 16, v46
	v_pk_add_f32 v[42:43], v[42:43], v[50:51]
	s_waitcnt lgkmcnt(0)
	v_pk_fma_f32 v[34:35], v[34:35], v[38:39], v[42:43]
	v_and_b32_e32 v39, 0xffff0000, v47
	v_lshlrev_b32_e32 v38, 16, v47
	v_pk_add_f32 v[38:39], v[44:45], v[38:39]
	s_nop 0
	v_pk_fma_f32 v[36:37], v[36:37], v[40:41], v[38:39]
	global_store_dwordx4 v[48:49], v[34:37], off
	s_nop 1
	v_or_b32_e32 v36, 8, v52
	v_lshlrev_b32_e32 v34, 12, v36
	v_lshlrev_b32_e32 v36, 11, v36
	v_mov_b32_e32 v37, v1
	v_mov_b32_e32 v35, v1
	v_lshl_add_u64 v[36:37], v[30:31], 0, v[36:37]
	v_lshl_add_u64 v[42:43], v[32:33], 0, v[34:35]
	s_waitcnt vmcnt(5)
	v_mov_b32_e32 v46, v186
	v_mov_b32_e32 v47, v187
	v_lshl_add_u64 v[48:49], v[28:29], 0, v[34:35]
	ds_read_b128 v[34:37], v0 offset:1152
	v_mov_b32_e32 v38, v180
	v_mov_b32_e32 v39, v181
	v_mov_b32_e32 v40, v182
	v_mov_b32_e32 v41, v183
	s_nop 0
	v_mov_b32_e32 v42, v200
	v_mov_b32_e32 v43, v201
	v_mov_b32_e32 v44, v202
	v_mov_b32_e32 v45, v203
	v_and_b32_e32 v51, 0xffff0000, v46
	v_lshlrev_b32_e32 v50, 16, v46
	v_pk_add_f32 v[42:43], v[42:43], v[50:51]
	s_waitcnt lgkmcnt(0)
	v_pk_fma_f32 v[34:35], v[34:35], v[38:39], v[42:43]
	v_and_b32_e32 v39, 0xffff0000, v47
	v_lshlrev_b32_e32 v38, 16, v47
	v_pk_add_f32 v[38:39], v[44:45], v[38:39]
	s_nop 0
	v_pk_fma_f32 v[36:37], v[36:37], v[40:41], v[38:39]
	global_store_dwordx4 v[48:49], v[34:37], off
	s_nop 1
	v_or_b32_e32 v36, 16, v52
	v_lshlrev_b32_e32 v34, 12, v36
	v_lshlrev_b32_e32 v36, 11, v36
	v_mov_b32_e32 v37, v1
	v_mov_b32_e32 v35, v1
	v_lshl_add_u64 v[36:37], v[30:31], 0, v[36:37]
	v_lshl_add_u64 v[42:43], v[32:33], 0, v[34:35]
	s_waitcnt vmcnt(4)
	v_mov_b32_e32 v46, v188
	v_mov_b32_e32 v47, v189
	v_lshl_add_u64 v[48:49], v[28:29], 0, v[34:35]
	ds_read_b128 v[34:37], v0 offset:2304
	v_mov_b32_e32 v38, v180
	v_mov_b32_e32 v39, v181
	v_mov_b32_e32 v40, v182
	v_mov_b32_e32 v41, v183
	s_nop 0
	v_mov_b32_e32 v42, v204
	v_mov_b32_e32 v43, v205
	v_mov_b32_e32 v44, v206
	v_mov_b32_e32 v45, v207
	v_and_b32_e32 v51, 0xffff0000, v46
	v_lshlrev_b32_e32 v50, 16, v46
	v_pk_add_f32 v[42:43], v[42:43], v[50:51]
	s_waitcnt lgkmcnt(0)
	v_pk_fma_f32 v[34:35], v[34:35], v[38:39], v[42:43]
	v_and_b32_e32 v39, 0xffff0000, v47
	v_lshlrev_b32_e32 v38, 16, v47
	v_pk_add_f32 v[38:39], v[44:45], v[38:39]
	s_nop 0
	v_pk_fma_f32 v[36:37], v[36:37], v[40:41], v[38:39]
	v_or_b32_e32 v38, 24, v52
	global_store_dwordx4 v[48:49], v[34:37], off
	s_nop 1
	v_lshlrev_b32_e32 v34, 12, v38
	v_mov_b32_e32 v35, v1
	v_lshl_add_u64 v[36:37], v[32:33], 0, v[34:35]
	v_lshlrev_b32_e32 v32, 11, v38
	v_mov_b32_e32 v33, v1
	v_lshl_add_u64 v[30:31], v[30:31], 0, v[32:33]
	s_waitcnt vmcnt(3)
	v_mov_b32_e32 v40, v190
	v_mov_b32_e32 v41, v191
	v_lshl_add_u64 v[42:43], v[28:29], 0, v[34:35]
	ds_read_b128 v[28:31], v0 offset:3456
	v_mov_b32_e32 v32, v180
	v_mov_b32_e32 v33, v181
	v_mov_b32_e32 v34, v182
	v_mov_b32_e32 v35, v183
	s_nop 0
	v_mov_b32_e32 v36, v208
	v_mov_b32_e32 v37, v209
	v_mov_b32_e32 v38, v210
	v_mov_b32_e32 v39, v211
	v_and_b32_e32 v27, 0xffff0000, v40
	v_lshlrev_b32_e32 v26, 16, v40
	v_pk_add_f32 v[26:27], v[36:37], v[26:27]
	s_waitcnt lgkmcnt(0)
	v_pk_fma_f32 v[26:27], v[28:29], v[32:33], v[26:27]
	v_and_b32_e32 v29, 0xffff0000, v41
	v_lshlrev_b32_e32 v28, 16, v41
	v_pk_add_f32 v[28:29], v[38:39], v[28:29]
	s_nop 0
	v_pk_fma_f32 v[28:29], v[30:31], v[34:35], v[28:29]
	global_store_dwordx4 v[42:43], v[26:29], off
	v_mov_b32_e32 v0, v179
	s_nop 0
	v_and_b32_e32 v26, 31, v0
	v_bfe_u32 v27, v0, 5, 1
	v_mul_u32_u24_e32 v27, 0x240, v27
	v_lshlrev_b32_e32 v26, 2, v26
	v_add3_u32 v26, v151, v27, v26
	ds_write2_b32 v26, v2, v3 offset1:36
	ds_write2_b32 v26, v4, v5 offset0:72 offset1:108
	v_add_u32_e32 v2, 0x400, v26
	ds_write2_b32 v2, v6, v7 offset0:32 offset1:68
	ds_write2_b32 v2, v8, v9 offset0:104 offset1:140
	v_add_u32_e32 v2, 0x800, v26
	ds_write2_b32 v2, v10, v11 offset0:64 offset1:100
	ds_write2_b32 v2, v12, v13 offset0:136 offset1:172
	v_add_u32_e32 v2, 0xc00, v26
	ds_write2_b32 v2, v14, v15 offset0:96 offset1:132
	ds_write2_b32 v2, v16, v17 offset0:168 offset1:204
	v_lshlrev_b32_e32 v2, 2, v0
	v_and_b32_e32 v4, 28, v2
	v_lshlrev_b32_e32 v10, 2, v4
	v_lshlrev_b32_e32 v4, 1, v4
	v_mov_b32_e32 v5, v1
	v_bfe_u32 v28, v0, 3, 3
	v_mov_b32_e32 v11, v1
	v_lshl_add_u64 v[6:7], v[18:19], 0, v[4:5]
	v_mul_u32_u24_e32 v0, 0x90, v28
	v_lshlrev_b32_e32 v12, 11, v28
	v_mov_b32_e32 v13, v1
	s_waitcnt lgkmcnt(0)
	v_lshl_add_u64 v[2:3], v[20:21], 0, v[10:11]
	v_lshl_add_u64 v[8:9], v[24:25], 0, v[10:11]
	v_lshl_add_u64 v[4:5], v[22:23], 0, v[10:11]
	v_add3_u32 v0, v151, v10, v0
	v_lshlrev_b32_e32 v10, 12, v28
	v_lshl_add_u64 v[12:13], v[6:7], 0, v[12:13]
	v_lshl_add_u64 v[2:3], v[2:3], 0, v[98:99]
	v_lshl_add_u64 v[18:19], v[8:9], 0, v[10:11]
	global_load_dwordx4 v[180:183], v[2:3], off
	v_mov_b32_e32 v212, v28
	v_lshlrev_b32_e32 v184, 11, v212
	v_mov_b32_e32 v185, v1
	v_lshl_add_u64 v[184:185], v[6:7], 0, v[184:185]
	global_load_dwordx2 v[184:185], v[184:185], off offset:64
	v_lshlrev_b32_e32 v192, 12, v212
	v_mov_b32_e32 v193, v1
	v_lshl_add_u64 v[192:193], v[8:9], 0, v[192:193]
	global_load_dwordx4 v[192:195], v[192:193], off offset:128
	v_or_b32_e32 v212, 8, v28
	v_lshlrev_b32_e32 v186, 11, v212
	v_mov_b32_e32 v187, v1
	v_lshl_add_u64 v[186:187], v[6:7], 0, v[186:187]
	global_load_dwordx2 v[186:187], v[186:187], off offset:64
	v_lshlrev_b32_e32 v200, 12, v212
	v_mov_b32_e32 v201, v1
	v_lshl_add_u64 v[200:201], v[8:9], 0, v[200:201]
	global_load_dwordx4 v[200:203], v[200:201], off offset:128
	v_or_b32_e32 v212, 16, v28
	v_lshlrev_b32_e32 v188, 11, v212
	v_mov_b32_e32 v189, v1
	v_lshl_add_u64 v[188:189], v[6:7], 0, v[188:189]
	global_load_dwordx2 v[188:189], v[188:189], off offset:64
	v_lshlrev_b32_e32 v204, 12, v212
	v_mov_b32_e32 v205, v1
	v_lshl_add_u64 v[204:205], v[8:9], 0, v[204:205]
	global_load_dwordx4 v[204:207], v[204:205], off offset:128
	v_or_b32_e32 v212, 24, v28
	v_lshlrev_b32_e32 v190, 11, v212
	v_mov_b32_e32 v191, v1
	v_lshl_add_u64 v[190:191], v[6:7], 0, v[190:191]
	global_load_dwordx2 v[190:191], v[190:191], off offset:64
	v_lshlrev_b32_e32 v208, 12, v212
	v_mov_b32_e32 v209, v1
	v_lshl_add_u64 v[208:209], v[8:9], 0, v[208:209]
	global_load_dwordx4 v[208:211], v[208:209], off offset:128
	s_waitcnt vmcnt(6)
	v_mov_b32_e32 v22, v184
	v_mov_b32_e32 v23, v185
	v_lshl_add_u64 v[24:25], v[4:5], 0, v[10:11]
	ds_read_b128 v[10:13], v0
	v_mov_b32_e32 v14, v180
	v_mov_b32_e32 v15, v181
	v_mov_b32_e32 v16, v182
	v_mov_b32_e32 v17, v183
	s_nop 0
	v_mov_b32_e32 v18, v192
	v_mov_b32_e32 v19, v193
	v_mov_b32_e32 v20, v194
	v_mov_b32_e32 v21, v195
	v_and_b32_e32 v27, 0xffff0000, v22
	v_lshlrev_b32_e32 v26, 16, v22
	v_pk_add_f32 v[18:19], v[18:19], v[26:27]
	s_waitcnt lgkmcnt(0)
	v_pk_fma_f32 v[10:11], v[10:11], v[14:15], v[18:19]
	v_and_b32_e32 v15, 0xffff0000, v23
	v_lshlrev_b32_e32 v14, 16, v23
	v_pk_add_f32 v[14:15], v[20:21], v[14:15]
	s_nop 0
	v_pk_fma_f32 v[12:13], v[12:13], v[16:17], v[14:15]
	global_store_dwordx4 v[24:25], v[10:13], off offset:128
	s_nop 1
	v_or_b32_e32 v12, 8, v28
	v_lshlrev_b32_e32 v10, 12, v12
	v_lshlrev_b32_e32 v12, 11, v12
	v_mov_b32_e32 v13, v1
	v_mov_b32_e32 v11, v1
	v_lshl_add_u64 v[12:13], v[6:7], 0, v[12:13]
	v_lshl_add_u64 v[18:19], v[8:9], 0, v[10:11]
	s_waitcnt vmcnt(5)
	v_mov_b32_e32 v22, v186
	v_mov_b32_e32 v23, v187
	v_lshl_add_u64 v[24:25], v[4:5], 0, v[10:11]
	ds_read_b128 v[10:13], v0 offset:1152
	v_mov_b32_e32 v14, v180
	v_mov_b32_e32 v15, v181
	v_mov_b32_e32 v16, v182
	v_mov_b32_e32 v17, v183
	s_nop 0
	v_mov_b32_e32 v18, v200
	v_mov_b32_e32 v19, v201
	v_mov_b32_e32 v20, v202
	v_mov_b32_e32 v21, v203
	v_and_b32_e32 v27, 0xffff0000, v22
	v_lshlrev_b32_e32 v26, 16, v22
	v_pk_add_f32 v[18:19], v[18:19], v[26:27]
	s_waitcnt lgkmcnt(0)
	v_pk_fma_f32 v[10:11], v[10:11], v[14:15], v[18:19]
	v_and_b32_e32 v15, 0xffff0000, v23
	v_lshlrev_b32_e32 v14, 16, v23
	v_pk_add_f32 v[14:15], v[20:21], v[14:15]
	s_nop 0
	v_pk_fma_f32 v[12:13], v[12:13], v[16:17], v[14:15]
	global_store_dwordx4 v[24:25], v[10:13], off offset:128
	s_nop 1
	v_or_b32_e32 v12, 16, v28
	v_lshlrev_b32_e32 v10, 12, v12
	v_lshlrev_b32_e32 v12, 11, v12
	v_mov_b32_e32 v13, v1
	v_mov_b32_e32 v11, v1
	v_lshl_add_u64 v[12:13], v[6:7], 0, v[12:13]
	v_lshl_add_u64 v[18:19], v[8:9], 0, v[10:11]
	s_waitcnt vmcnt(4)
	v_mov_b32_e32 v22, v188
	v_mov_b32_e32 v23, v189
	v_lshl_add_u64 v[24:25], v[4:5], 0, v[10:11]
	ds_read_b128 v[10:13], v0 offset:2304
	v_mov_b32_e32 v14, v180
	v_mov_b32_e32 v15, v181
	v_mov_b32_e32 v16, v182
	v_mov_b32_e32 v17, v183
	s_nop 0
	v_mov_b32_e32 v18, v204
	v_mov_b32_e32 v19, v205
	v_mov_b32_e32 v20, v206
	v_mov_b32_e32 v21, v207
	v_and_b32_e32 v27, 0xffff0000, v22
	v_lshlrev_b32_e32 v26, 16, v22
	v_pk_add_f32 v[18:19], v[18:19], v[26:27]
	s_waitcnt lgkmcnt(0)
	v_pk_fma_f32 v[10:11], v[10:11], v[14:15], v[18:19]
	v_and_b32_e32 v15, 0xffff0000, v23
	v_lshlrev_b32_e32 v14, 16, v23
	v_pk_add_f32 v[14:15], v[20:21], v[14:15]
	s_nop 0
	v_pk_fma_f32 v[12:13], v[12:13], v[16:17], v[14:15]
	v_or_b32_e32 v14, 24, v28
	global_store_dwordx4 v[24:25], v[10:13], off offset:128
	s_nop 1
	v_lshlrev_b32_e32 v10, 12, v14
	v_mov_b32_e32 v11, v1
	v_lshl_add_u64 v[12:13], v[8:9], 0, v[10:11]
	v_lshlrev_b32_e32 v8, 11, v14
	v_mov_b32_e32 v9, v1
	v_lshl_add_u64 v[6:7], v[6:7], 0, v[8:9]
	s_waitcnt vmcnt(3)
	v_mov_b32_e32 v16, v190
	v_mov_b32_e32 v17, v191
	v_lshl_add_u64 v[18:19], v[4:5], 0, v[10:11]
	ds_read_b128 v[4:7], v0 offset:3456
	v_mov_b32_e32 v8, v180
	v_mov_b32_e32 v9, v181
	v_mov_b32_e32 v10, v182
	v_mov_b32_e32 v11, v183
	s_nop 0
	v_mov_b32_e32 v12, v208
	v_mov_b32_e32 v13, v209
	v_mov_b32_e32 v14, v210
	v_mov_b32_e32 v15, v211
	v_and_b32_e32 v3, 0xffff0000, v16
	v_lshlrev_b32_e32 v2, 16, v16
	v_pk_add_f32 v[2:3], v[12:13], v[2:3]
	s_waitcnt lgkmcnt(0)
	v_pk_fma_f32 v[2:3], v[4:5], v[8:9], v[2:3]
	v_and_b32_e32 v5, 0xffff0000, v17
	v_lshlrev_b32_e32 v4, 16, v17
	v_pk_add_f32 v[4:5], v[14:15], v[4:5]
	s_nop 0
	v_pk_fma_f32 v[4:5], v[6:7], v[10:11], v[4:5]
	global_store_dwordx4 v[18:19], v[2:5], off offset:128
	s_add_i32 s7, s7, s6
	s_cmpk_gt_i32 s7, 0x1ff
	v_readlane_b32 s64, v254, 55
	v_readlane_b32 s38, v254, 57
	v_readlane_b32 s42, v254, 59
	s_cselect_b64 s[0:1], -1, 0
	v_readlane_b32 s65, v254, 56
	v_readlane_b32 s39, v254, 58
	v_readlane_b32 s43, v254, 60
	s_mov_b32 s51, s27
	s_movk_i32 s37, 0x1000
	s_movk_i32 s36, 0x1ff
	s_mov_b32 s47, 0x7f800000
	s_mov_b32 s49, 0x20000
	s_mov_b32 s46, 0x4081e0d3
	s_mov_b32 s48, 0xc09de9e6
	s_mov_b64 s[44:45], 0x800
	s_branch .LBB0_21
